# loop-edge rotation (7.11): in the four big GEMM K-loops the counter / pointer bump / exit compare moved in front of the loop-back barrier (on top of v13)
# speedup vs baseline: 1.0110x; 1.0110x over previous
; #define PG8_STAGE(bufoff, gbase, voff) do { _Pragma("unroll") for (int _i = 0; _i < 2; ++_i) \
;         __builtin_amdgcn_global_load_lds((const unsigned*)((const char*)(gbase) + (voff)[_i]), (PG8_LAS unsigned*)(lds + (bufoff) + ldsw + _i * 8192), 16, 0, 0); } while (0)
; #define PG8_LDA(dst, b, h) do { _Pragma("unroll") for (int m = 0; m < 4; ++m) _Pragma("unroll") for (int k = 0; k < 2; ++k) dst[m][k] = *(const PG8_LAS bf16x8*)(lds + PG8_SA(b, h) + aoff + m * 2048 + k * 1024); } while (0)
; #define PG8_LDB(dst, b, h) do { _Pragma("unroll") for (int n = 0; n < 2; ++n) _Pragma("unroll") for (int k = 0; k < 2; ++k) dst[n][k] = *(const PG8_LAS bf16x8*)(lds + PG8_SB(b, h) + boff + n * 2048 + k * 1024); } while (0)
; #define PG8_MMA(ai, bj, At, Bt) do { __builtin_amdgcn_s_setprio(1); _Pragma("unroll") for (int m = 0; m < 4; ++m) _Pragma("unroll") for (int n = 0; n < 2; ++n) _Pragma("unroll") for (int k = 0; k < 2; ++k) \
;         acc[ai][bj][m][n] = __builtin_amdgcn_mfma_f32_16x16x32_bf16(Bt[n][k], At[m][k], acc[ai][bj][m][n], 0, 0, 0); __builtin_amdgcn_s_setprio(0); } while (0)
; #define PG8_WAIT_V(n) asm volatile("s_waitcnt vmcnt(" #n ")" ::: "memory")
; #define PG8_BAR __builtin_amdgcn_s_barrier()
; template <class Epi, class Sched, bool ALIGN_EPI = false, bool SP2 = false>
; __device__ __forceinline__ void gemm_phase(PG8_LAS unsigned char* lds, const Gemm g, const Sched& S, const Epi& E) {
;     ...
;         for (int t = 0; t < nt; t += 2) {
;             const bool last = (t == nt - 2);
;             const char* a1 = cA + (size_t)(t + 1) * kstep;
;             const char* a2 = last ? nA : cA + (size_t)(t + 2) * kstep; const char* b2 = last ? nB : cB + (size_t)(t + 2) * kstep;
;             const char* a3 = a2 + kstep; const char* b3 = b2 + kstep;
;             if (last && has_next) S.a_ready(nxt);
;             if constexpr (SP2) {
;             PG8_LDB(B0, 0, 0); PG8_LDB(B1, 0, 1); PG8_SCHED; PG8_LDA(At, 0, 0); PG8_STAGE(PG8_SA(1, 1), a1 + hstep, voffA);
;             PG8_WAIT_V(8); PG8_WAIT_L(0); PG8_BAR; PG8_MMA(0, 0, At, B0); PG8_MMA(0, 1, At, B1); PG8_BAR; PG8_SCHED;
;             PG8_LDA(At, 0, 1); PG8_STAGE(PG8_SB(0, 0), b2, voffB); PG8_STAGE(PG8_SB(0, 1), b2 + hstep, voffB); PG8_STAGE(PG8_SA(0, 0), a2, voffA);
;             PG8_WAIT_V(8); PG8_WAIT_L(0); PG8_BAR; PG8_MMA(1, 0, At, B0); PG8_MMA(1, 1, At, B1); PG8_BAR; PG8_SCHED;
.LBB0_234:
	s_add_u32 s6, s4, 0xfffc0080
	s_addc_u32 s7, s5, -1
	s_add_i32 s58, 0, 0x10000
	s_cmp_eq_u32 s57, 12
	s_cselect_b32 s17, s9, s7
	s_cselect_b32 s16, s11, s6
	v_add_u32_e32 v0, s58, v164
	s_cselect_b32 s7, s25, s56
	s_cselect_b32 s6, s52, s53
	s_add_i32 s69, 0, 0x14000
	ds_read_b128 v[130:133], v0
	ds_read_b128 v[134:137], v0 offset:1024
	ds_read_b128 v[138:141], v0 offset:2048
	ds_read_b128 v[142:145], v0 offset:3072
	v_add_u32_e32 v0, s69, v164
	ds_read_b128 v[158:161], v0
	ds_read_b128 v[166:169], v0 offset:1024
	ds_read_b128 v[170:173], v0 offset:2048
	ds_read_b128 v[174:177], v0 offset:3072
	v_lshl_add_u64 v[162:163], s[4:5], 0, v[154:155]
	s_add_i32 m0, s13, 0xc000
	ds_read_b128 v[178:181], v165
	ds_read_b128 v[182:185], v165 offset:1024
	ds_read_b128 v[186:189], v165 offset:2048
	ds_read_b128 v[190:193], v165 offset:3072
	ds_read_b128 v[218:221], v165 offset:4096
	ds_read_b128 v[222:225], v165 offset:5120
	ds_read_b128 v[226:229], v165 offset:6144
	ds_read_b128 v[230:233], v165 offset:7168
	global_load_lds_dwordx4 v[162:163], off
	v_lshl_add_u64 v[162:163], s[4:5], 0, v[156:157]
	s_add_i32 m0, s13, 0xe000
	s_nop 0
	global_load_lds_dwordx4 v[162:163], off
	s_waitcnt vmcnt(8)
	s_waitcnt lgkmcnt(0)
	s_barrier
	s_setprio 1
	s_waitcnt lgkmcnt(0)
	v_mfma_f32_16x16x32_bf16 v[62:65], v[130:133], v[178:181], v[62:65]
	v_mfma_f32_16x16x32_bf16 v[58:61], v[138:141], v[178:181], v[58:61]
	v_mfma_f32_16x16x32_bf16 v[54:57], v[130:133], v[186:189], v[54:57]
	v_mfma_f32_16x16x32_bf16 v[50:53], v[138:141], v[186:189], v[50:53]
	v_mfma_f32_16x16x32_bf16 v[46:49], v[130:133], v[218:221], v[46:49]
	v_mfma_f32_16x16x32_bf16 v[42:45], v[138:141], v[218:221], v[42:45]
	v_mfma_f32_16x16x32_bf16 v[38:41], v[130:133], v[226:229], v[38:41]
	v_mfma_f32_16x16x32_bf16 v[34:37], v[138:141], v[226:229], v[34:37]
	v_mfma_f32_16x16x32_bf16 v[62:65], v[134:137], v[182:185], v[62:65]
	v_mfma_f32_16x16x32_bf16 v[58:61], v[142:145], v[182:185], v[58:61]
	v_mfma_f32_16x16x32_bf16 v[54:57], v[134:137], v[190:193], v[54:57]
	v_mfma_f32_16x16x32_bf16 v[50:53], v[142:145], v[190:193], v[50:53]
	v_mfma_f32_16x16x32_bf16 v[46:49], v[134:137], v[222:225], v[46:49]
	v_mfma_f32_16x16x32_bf16 v[42:45], v[142:145], v[222:225], v[42:45]
	v_mfma_f32_16x16x32_bf16 v[38:41], v[134:137], v[230:233], v[38:41]
	v_mfma_f32_16x16x32_bf16 v[34:37], v[142:145], v[230:233], v[34:37]
	s_setprio 0
	s_setprio 1
	v_mfma_f32_16x16x32_bf16 v[126:129], v[158:161], v[178:181], v[126:129]
	v_mfma_f32_16x16x32_bf16 v[122:125], v[170:173], v[178:181], v[122:125]
	v_mfma_f32_16x16x32_bf16 v[118:121], v[158:161], v[186:189], v[118:121]
	v_mfma_f32_16x16x32_bf16 v[114:117], v[170:173], v[186:189], v[114:117]
	v_mfma_f32_16x16x32_bf16 v[110:113], v[158:161], v[218:221], v[110:113]
	v_mfma_f32_16x16x32_bf16 v[106:109], v[170:173], v[218:221], v[106:109]
	v_mfma_f32_16x16x32_bf16 v[102:105], v[158:161], v[226:229], v[102:105]
	v_mfma_f32_16x16x32_bf16 v[98:101], v[170:173], v[226:229], v[98:101]
	v_mfma_f32_16x16x32_bf16 v[126:129], v[166:169], v[182:185], v[126:129]
	v_mfma_f32_16x16x32_bf16 v[122:125], v[174:177], v[182:185], v[122:125]
	v_mfma_f32_16x16x32_bf16 v[118:121], v[166:169], v[190:193], v[118:121]
	v_mfma_f32_16x16x32_bf16 v[114:117], v[174:177], v[190:193], v[114:117]
	v_mfma_f32_16x16x32_bf16 v[110:113], v[166:169], v[222:225], v[110:113]
	v_mfma_f32_16x16x32_bf16 v[106:109], v[174:177], v[222:225], v[106:109]
	v_mfma_f32_16x16x32_bf16 v[102:105], v[166:169], v[230:233], v[102:105]
	v_mfma_f32_16x16x32_bf16 v[98:101], v[174:177], v[230:233], v[98:101]
	s_setprio 0
	s_barrier
	s_add_i32 s58, s58, s12
	v_lshl_add_u64 v[162:163], s[6:7], 0, v[148:149]
	s_mov_b32 m0, s58
	ds_read_b128 v[178:181], v165 offset:16384
	ds_read_b128 v[182:185], v165 offset:17408
	ds_read_b128 v[186:189], v165 offset:18432
	ds_read_b128 v[190:193], v165 offset:19456
	ds_read_b128 v[218:221], v165 offset:20480
	ds_read_b128 v[222:225], v165 offset:21504
	ds_read_b128 v[226:229], v165 offset:22528
	ds_read_b128 v[230:233], v165 offset:23552
	global_load_lds_dwordx4 v[162:163], off
	s_add_i32 m0, s58, 0x2000
	s_add_u32 s58, s6, 0x40000
	v_lshl_add_u64 v[194:195], s[6:7], 0, v[152:153]
	s_addc_u32 s59, s7, 0
	s_add_i32 s69, s69, s12
	global_load_lds_dwordx4 v[194:195], off
	v_lshl_add_u64 v[196:197], s[58:59], 0, v[148:149]
	s_mov_b32 m0, s69
	v_lshl_add_u64 v[198:199], s[16:17], 0, v[150:151]
	global_load_lds_dwordx4 v[196:197], off
	v_lshl_add_u64 v[196:197], s[58:59], 0, v[152:153]
	s_add_i32 m0, s69, 0x2000
	s_nop 0
	global_load_lds_dwordx4 v[196:197], off
	v_lshl_add_u64 v[196:197], s[16:17], 0, v[146:147]
	s_mov_b32 m0, s13
	s_nop 0
	global_load_lds_dwordx4 v[196:197], off
	s_mov_b32 m0, s50
	s_nop 0
	global_load_lds_dwordx4 v[198:199], off
	s_waitcnt vmcnt(8)
	s_waitcnt lgkmcnt(0)
	s_barrier
; #define PG8_STAGE(bufoff, gbase, voff) do { _Pragma("unroll") for (int _i = 0; _i < 2; ++_i) \
;         __builtin_amdgcn_global_load_lds((const unsigned*)((const char*)(gbase) + (voff)[_i]), (PG8_LAS unsigned*)(lds + (bufoff) + ldsw + _i * 8192), 16, 0, 0); } while (0)
; #define PG8_LDA(dst, b, h) do { _Pragma("unroll") for (int m = 0; m < 4; ++m) _Pragma("unroll") for (int k = 0; k < 2; ++k) dst[m][k] = *(const PG8_LAS bf16x8*)(lds + PG8_SA(b, h) + aoff + m * 2048 + k * 1024); } while (0)
; #define PG8_LDB(dst, b, h) do { _Pragma("unroll") for (int n = 0; n < 2; ++n) _Pragma("unroll") for (int k = 0; k < 2; ++k) dst[n][k] = *(const PG8_LAS bf16x8*)(lds + PG8_SB(b, h) + boff + n * 2048 + k * 1024); } while (0)
; #define PG8_MMA(ai, bj, At, Bt) do { __builtin_amdgcn_s_setprio(1); _Pragma("unroll") for (int m = 0; m < 4; ++m) _Pragma("unroll") for (int n = 0; n < 2; ++n) _Pragma("unroll") for (int k = 0; k < 2; ++k) \
;         acc[ai][bj][m][n] = __builtin_amdgcn_mfma_f32_16x16x32_bf16(Bt[n][k], At[m][k], acc[ai][bj][m][n], 0, 0, 0); __builtin_amdgcn_s_setprio(0); } while (0)
; #define PG8_WAIT_V(n) asm volatile("s_waitcnt vmcnt(" #n ")" ::: "memory")
; #define PG8_WAIT_L(n) asm volatile("s_waitcnt lgkmcnt(" #n ")" ::: "memory")
; #define PG8_BAR __builtin_amdgcn_s_barrier()
; #define PG8_SCHED __builtin_amdgcn_sched_barrier(0)
; template <class Epi, class Sched, bool ALIGN_EPI = false, bool SP2 = false>
; __device__ __forceinline__ void gemm_phase(PG8_LAS unsigned char* lds, const Gemm g, const Sched& S, const Epi& E) {
;     ...
;             PG8_WAIT_V(8); PG8_WAIT_L(0); PG8_BAR; PG8_MMA(1, 0, At, B0); PG8_MMA(1, 1, At, B1); PG8_BAR; PG8_SCHED;
;             PG8_LDB(B0, 1, 0); PG8_LDB(B1, 1, 1); PG8_SCHED; PG8_LDA(At, 1, 0); PG8_STAGE(PG8_SA(0, 1), a2 + hstep, voffA);
;             PG8_WAIT_V(8); PG8_WAIT_L(0); PG8_BAR; PG8_MMA(0, 0, At, B0); PG8_MMA(0, 1, At, B1); PG8_BAR; PG8_SCHED;
	s_setprio 1
	s_waitcnt lgkmcnt(0)
	v_mfma_f32_16x16x32_bf16 v[30:33], v[130:133], v[178:181], v[30:33]
	v_mfma_f32_16x16x32_bf16 v[26:29], v[138:141], v[178:181], v[26:29]
	v_mfma_f32_16x16x32_bf16 v[22:25], v[130:133], v[186:189], v[22:25]
	v_mfma_f32_16x16x32_bf16 v[18:21], v[138:141], v[186:189], v[18:21]
	v_mfma_f32_16x16x32_bf16 v[14:17], v[130:133], v[218:221], v[14:17]
	v_mfma_f32_16x16x32_bf16 v[10:13], v[138:141], v[218:221], v[10:13]
	v_mfma_f32_16x16x32_bf16 v[6:9], v[130:133], v[226:229], v[6:9]
	v_mfma_f32_16x16x32_bf16 v[2:5], v[138:141], v[226:229], v[2:5]
	v_mfma_f32_16x16x32_bf16 v[30:33], v[134:137], v[182:185], v[30:33]
	v_mfma_f32_16x16x32_bf16 v[26:29], v[142:145], v[182:185], v[26:29]
	v_mfma_f32_16x16x32_bf16 v[22:25], v[134:137], v[190:193], v[22:25]
	v_mfma_f32_16x16x32_bf16 v[18:21], v[142:145], v[190:193], v[18:21]
	v_mfma_f32_16x16x32_bf16 v[14:17], v[134:137], v[222:225], v[14:17]
	v_mfma_f32_16x16x32_bf16 v[10:13], v[142:145], v[222:225], v[10:13]
	v_mfma_f32_16x16x32_bf16 v[6:9], v[134:137], v[230:233], v[6:9]
	v_mfma_f32_16x16x32_bf16 v[2:5], v[142:145], v[230:233], v[2:5]
	s_setprio 0
	s_setprio 1
	v_mfma_f32_16x16x32_bf16 v[94:97], v[158:161], v[178:181], v[94:97]
	v_mfma_f32_16x16x32_bf16 v[90:93], v[170:173], v[178:181], v[90:93]
	v_mfma_f32_16x16x32_bf16 v[86:89], v[158:161], v[186:189], v[86:89]
	v_mfma_f32_16x16x32_bf16 v[82:85], v[170:173], v[186:189], v[82:85]
	v_mfma_f32_16x16x32_bf16 v[78:81], v[158:161], v[218:221], v[78:81]
	v_mfma_f32_16x16x32_bf16 v[74:77], v[170:173], v[218:221], v[74:77]
	v_mfma_f32_16x16x32_bf16 v[70:73], v[158:161], v[226:229], v[70:73]
	v_mfma_f32_16x16x32_bf16 v[66:69], v[170:173], v[226:229], v[66:69]
	v_mfma_f32_16x16x32_bf16 v[94:97], v[166:169], v[182:185], v[94:97]
	v_mfma_f32_16x16x32_bf16 v[90:93], v[174:177], v[182:185], v[90:93]
	v_mfma_f32_16x16x32_bf16 v[86:89], v[166:169], v[190:193], v[86:89]
	v_mfma_f32_16x16x32_bf16 v[82:85], v[174:177], v[190:193], v[82:85]
	v_mfma_f32_16x16x32_bf16 v[78:81], v[166:169], v[222:225], v[78:81]
	v_mfma_f32_16x16x32_bf16 v[74:77], v[174:177], v[222:225], v[74:77]
	v_mfma_f32_16x16x32_bf16 v[70:73], v[166:169], v[230:233], v[70:73]
	v_mfma_f32_16x16x32_bf16 v[66:69], v[174:177], v[230:233], v[66:69]
	s_setprio 0
	s_barrier
	s_add_i32 s58, 0, 0x18000
	v_add_u32_e32 v0, s58, v164
	s_add_i32 s59, 0, 0x1c000
	ds_read_b128 v[130:133], v0
	ds_read_b128 v[134:137], v0 offset:1024
	ds_read_b128 v[138:141], v0 offset:2048
	ds_read_b128 v[142:145], v0 offset:3072
	v_add_u32_e32 v0, s59, v164
	ds_read_b128 v[158:161], v0
	ds_read_b128 v[166:169], v0 offset:1024
	ds_read_b128 v[170:173], v0 offset:2048
	ds_read_b128 v[174:177], v0 offset:3072
	s_add_u32 s16, s16, 0x40000
	s_addc_u32 s17, s17, 0
	s_mov_b32 m0, s51
	v_lshl_add_u64 v[202:203], s[16:17], 0, v[146:147]
	ds_read_b128 v[178:181], v165 offset:32768
	ds_read_b128 v[182:185], v165 offset:33792
	ds_read_b128 v[186:189], v165 offset:34816
	ds_read_b128 v[190:193], v165 offset:35840
	ds_read_b128 v[218:221], v165 offset:36864
	ds_read_b128 v[222:225], v165 offset:37888
	ds_read_b128 v[226:229], v165 offset:38912
	ds_read_b128 v[230:233], v165 offset:39936
	global_load_lds_dwordx4 v[202:203], off
	v_lshl_add_u64 v[202:203], s[16:17], 0, v[150:151]
	s_mov_b32 m0, s18
	s_nop 0
	global_load_lds_dwordx4 v[202:203], off
	s_waitcnt vmcnt(8)
	s_waitcnt lgkmcnt(0)
	s_barrier
	s_setprio 1
	s_waitcnt lgkmcnt(0)
	v_mfma_f32_16x16x32_bf16 v[62:65], v[130:133], v[178:181], v[62:65]
	v_mfma_f32_16x16x32_bf16 v[58:61], v[138:141], v[178:181], v[58:61]
	v_mfma_f32_16x16x32_bf16 v[54:57], v[130:133], v[186:189], v[54:57]
	v_mfma_f32_16x16x32_bf16 v[50:53], v[138:141], v[186:189], v[50:53]
	v_mfma_f32_16x16x32_bf16 v[46:49], v[130:133], v[218:221], v[46:49]
	v_mfma_f32_16x16x32_bf16 v[42:45], v[138:141], v[218:221], v[42:45]
	v_mfma_f32_16x16x32_bf16 v[38:41], v[130:133], v[226:229], v[38:41]
	v_mfma_f32_16x16x32_bf16 v[34:37], v[138:141], v[226:229], v[34:37]
	v_mfma_f32_16x16x32_bf16 v[62:65], v[134:137], v[182:185], v[62:65]
	v_mfma_f32_16x16x32_bf16 v[58:61], v[142:145], v[182:185], v[58:61]
	v_mfma_f32_16x16x32_bf16 v[54:57], v[134:137], v[190:193], v[54:57]
	v_mfma_f32_16x16x32_bf16 v[50:53], v[142:145], v[190:193], v[50:53]
	v_mfma_f32_16x16x32_bf16 v[46:49], v[134:137], v[222:225], v[46:49]
	v_mfma_f32_16x16x32_bf16 v[42:45], v[142:145], v[222:225], v[42:45]
	v_mfma_f32_16x16x32_bf16 v[38:41], v[134:137], v[230:233], v[38:41]
	v_mfma_f32_16x16x32_bf16 v[34:37], v[142:145], v[230:233], v[34:37]
	s_setprio 0
	s_setprio 1
	v_mfma_f32_16x16x32_bf16 v[126:129], v[158:161], v[178:181], v[126:129]
	v_mfma_f32_16x16x32_bf16 v[122:125], v[170:173], v[178:181], v[122:125]
	v_mfma_f32_16x16x32_bf16 v[118:121], v[158:161], v[186:189], v[118:121]
	v_mfma_f32_16x16x32_bf16 v[114:117], v[170:173], v[186:189], v[114:117]
	v_mfma_f32_16x16x32_bf16 v[110:113], v[158:161], v[218:221], v[110:113]
	v_mfma_f32_16x16x32_bf16 v[106:109], v[170:173], v[218:221], v[106:109]
	v_mfma_f32_16x16x32_bf16 v[102:105], v[158:161], v[226:229], v[102:105]
	v_mfma_f32_16x16x32_bf16 v[98:101], v[170:173], v[226:229], v[98:101]
	v_mfma_f32_16x16x32_bf16 v[126:129], v[166:169], v[182:185], v[126:129]
	v_mfma_f32_16x16x32_bf16 v[122:125], v[174:177], v[182:185], v[122:125]
	v_mfma_f32_16x16x32_bf16 v[118:121], v[166:169], v[190:193], v[118:121]
	v_mfma_f32_16x16x32_bf16 v[114:117], v[174:177], v[190:193], v[114:117]
	v_mfma_f32_16x16x32_bf16 v[110:113], v[166:169], v[222:225], v[110:113]
	v_mfma_f32_16x16x32_bf16 v[106:109], v[174:177], v[222:225], v[106:109]
	v_mfma_f32_16x16x32_bf16 v[102:105], v[166:169], v[230:233], v[102:105]
	v_mfma_f32_16x16x32_bf16 v[98:101], v[174:177], v[230:233], v[98:101]
	s_setprio 0
	s_barrier
; #define PG8_STAGE(bufoff, gbase, voff) do { _Pragma("unroll") for (int _i = 0; _i < 2; ++_i) \
;         __builtin_amdgcn_global_load_lds((const unsigned*)((const char*)(gbase) + (voff)[_i]), (PG8_LAS unsigned*)(lds + (bufoff) + ldsw + _i * 8192), 16, 0, 0); } while (0)
; #define PG8_LDA(dst, b, h) do { _Pragma("unroll") for (int m = 0; m < 4; ++m) _Pragma("unroll") for (int k = 0; k < 2; ++k) dst[m][k] = *(const PG8_LAS bf16x8*)(lds + PG8_SA(b, h) + aoff + m * 2048 + k * 1024); } while (0)
; #define PG8_MMA(ai, bj, At, Bt) do { __builtin_amdgcn_s_setprio(1); _Pragma("unroll") for (int m = 0; m < 4; ++m) _Pragma("unroll") for (int n = 0; n < 2; ++n) _Pragma("unroll") for (int k = 0; k < 2; ++k) \
;         acc[ai][bj][m][n] = __builtin_amdgcn_mfma_f32_16x16x32_bf16(Bt[n][k], At[m][k], acc[ai][bj][m][n], 0, 0, 0); __builtin_amdgcn_s_setprio(0); } while (0)
; #define PG8_WAIT_V(n) asm volatile("s_waitcnt vmcnt(" #n ")" ::: "memory")
; #define PG8_WAIT_L(n) asm volatile("s_waitcnt lgkmcnt(" #n ")" ::: "memory")
; #define PG8_BAR __builtin_amdgcn_s_barrier()
; #define PG8_SCHED __builtin_amdgcn_sched_barrier(0)
; template <class Epi, class Sched, bool ALIGN_EPI = false, bool SP2 = false>
; __device__ __forceinline__ void gemm_phase(PG8_LAS unsigned char* lds, const Gemm g, const Sched& S, const Epi& E) {
;     ...
;         for (int t = 0; t < nt; t += 2) {
;     ...
;             PG8_LDA(At, 1, 1); PG8_STAGE(PG8_SB(1, 0), b3, voffB); PG8_STAGE(PG8_SB(1, 1), b3 + hstep, voffB); PG8_STAGE(PG8_SA(1, 0), a3, voffA);
;             PG8_WAIT_V(8); PG8_WAIT_L(0); PG8_BAR; PG8_MMA(1, 0, At, B0); PG8_MMA(1, 1, At, B1); PG8_BAR; PG8_SCHED;
	s_add_i32 s16, s58, s12
	v_lshl_add_u64 v[162:163], v[162:163], 0, s[84:85]
	s_mov_b32 m0, s16
	ds_read_b128 v[178:181], v165 offset:49152
	ds_read_b128 v[182:185], v165 offset:50176
	ds_read_b128 v[186:189], v165 offset:51200
	ds_read_b128 v[190:193], v165 offset:52224
	ds_read_b128 v[218:221], v165 offset:53248
	ds_read_b128 v[222:225], v165 offset:54272
	ds_read_b128 v[226:229], v165 offset:55296
	ds_read_b128 v[230:233], v165 offset:56320
	global_load_lds_dwordx4 v[162:163], off
	s_add_i32 m0, s16, 0x2000
	s_add_u32 s6, s6, 0x40080
	v_lshl_add_u64 v[162:163], v[194:195], 0, s[84:85]
	s_addc_u32 s7, s7, 0
	s_add_i32 s16, s59, s12
	global_load_lds_dwordx4 v[162:163], off
	v_lshl_add_u64 v[162:163], s[6:7], 0, v[148:149]
	s_mov_b32 m0, s16
	s_nop 0
	global_load_lds_dwordx4 v[162:163], off
	v_lshl_add_u64 v[162:163], s[6:7], 0, v[152:153]
	s_add_i32 m0, s16, 0x2000
	s_nop 0
	global_load_lds_dwordx4 v[162:163], off
	v_lshl_add_u64 v[162:163], v[196:197], 0, s[84:85]
	s_mov_b32 m0, s97
	s_nop 0
	global_load_lds_dwordx4 v[162:163], off
	v_lshl_add_u64 v[162:163], v[198:199], 0, s[84:85]
	s_mov_b32 m0, s0
	s_nop 0
	global_load_lds_dwordx4 v[162:163], off
	s_waitcnt vmcnt(8)
	s_waitcnt lgkmcnt(0)
	s_barrier
	s_setprio 1
	s_waitcnt lgkmcnt(0)
	v_mfma_f32_16x16x32_bf16 v[30:33], v[130:133], v[178:181], v[30:33]
	v_mfma_f32_16x16x32_bf16 v[26:29], v[138:141], v[178:181], v[26:29]
	v_mfma_f32_16x16x32_bf16 v[22:25], v[130:133], v[186:189], v[22:25]
	v_mfma_f32_16x16x32_bf16 v[18:21], v[138:141], v[186:189], v[18:21]
	v_mfma_f32_16x16x32_bf16 v[14:17], v[130:133], v[218:221], v[14:17]
	v_mfma_f32_16x16x32_bf16 v[10:13], v[138:141], v[218:221], v[10:13]
	v_mfma_f32_16x16x32_bf16 v[6:9], v[130:133], v[226:229], v[6:9]
	v_mfma_f32_16x16x32_bf16 v[2:5], v[138:141], v[226:229], v[2:5]
	v_mfma_f32_16x16x32_bf16 v[30:33], v[134:137], v[182:185], v[30:33]
	v_mfma_f32_16x16x32_bf16 v[26:29], v[142:145], v[182:185], v[26:29]
	v_mfma_f32_16x16x32_bf16 v[22:25], v[134:137], v[190:193], v[22:25]
	v_mfma_f32_16x16x32_bf16 v[18:21], v[142:145], v[190:193], v[18:21]
	v_mfma_f32_16x16x32_bf16 v[14:17], v[134:137], v[222:225], v[14:17]
	v_mfma_f32_16x16x32_bf16 v[10:13], v[142:145], v[222:225], v[10:13]
	v_mfma_f32_16x16x32_bf16 v[6:9], v[134:137], v[230:233], v[6:9]
	v_mfma_f32_16x16x32_bf16 v[2:5], v[142:145], v[230:233], v[2:5]
	s_setprio 0
	s_setprio 1
	v_mfma_f32_16x16x32_bf16 v[94:97], v[158:161], v[178:181], v[94:97]
	v_mfma_f32_16x16x32_bf16 v[90:93], v[170:173], v[178:181], v[90:93]
	v_mfma_f32_16x16x32_bf16 v[86:89], v[158:161], v[186:189], v[86:89]
	v_mfma_f32_16x16x32_bf16 v[82:85], v[170:173], v[186:189], v[82:85]
	v_mfma_f32_16x16x32_bf16 v[78:81], v[158:161], v[218:221], v[78:81]
	v_mfma_f32_16x16x32_bf16 v[74:77], v[170:173], v[218:221], v[74:77]
	v_mfma_f32_16x16x32_bf16 v[70:73], v[158:161], v[226:229], v[70:73]
	v_mfma_f32_16x16x32_bf16 v[66:69], v[170:173], v[226:229], v[66:69]
	v_mfma_f32_16x16x32_bf16 v[94:97], v[166:169], v[182:185], v[94:97]
	v_mfma_f32_16x16x32_bf16 v[90:93], v[174:177], v[182:185], v[90:93]
	v_mfma_f32_16x16x32_bf16 v[86:89], v[166:169], v[190:193], v[86:89]
	v_mfma_f32_16x16x32_bf16 v[82:85], v[174:177], v[190:193], v[82:85]
	v_mfma_f32_16x16x32_bf16 v[78:81], v[166:169], v[222:225], v[78:81]
	v_mfma_f32_16x16x32_bf16 v[74:77], v[174:177], v[222:225], v[74:77]
	v_mfma_f32_16x16x32_bf16 v[70:73], v[166:169], v[230:233], v[70:73]
	v_mfma_f32_16x16x32_bf16 v[66:69], v[174:177], v[230:233], v[66:69]
	s_setprio 0
	s_add_i32 s57, s57, 2
	s_add_u32 s4, s4, 0x100
	s_addc_u32 s5, s5, 0
	s_add_u32 s53, s53, 0x100
	s_addc_u32 s56, s56, 0
	s_cmp_gt_u32 s57, 13
	s_barrier
	s_cbranch_scc0 .LBB0_234
	s_and_b64 vcc, exec, s[64:65]
	s_cbranch_vccz .LBB0_237
	s_barrier

; #define PG8_STAGE(bufoff, gbase, voff) do { _Pragma("unroll") for (int _i = 0; _i < 2; ++_i) \
;         __builtin_amdgcn_global_load_lds((const unsigned*)((const char*)(gbase) + (voff)[_i]), (PG8_LAS unsigned*)(lds + (bufoff) + ldsw + _i * 8192), 16, 0, 0); } while (0)
; #define PG8_LDA(dst, b, h) do { _Pragma("unroll") for (int m = 0; m < 4; ++m) _Pragma("unroll") for (int k = 0; k < 2; ++k) dst[m][k] = *(const PG8_LAS bf16x8*)(lds + PG8_SA(b, h) + aoff + m * 2048 + k * 1024); } while (0)
; #define PG8_LDB(dst, b, h) do { _Pragma("unroll") for (int n = 0; n < 2; ++n) _Pragma("unroll") for (int k = 0; k < 2; ++k) dst[n][k] = *(const PG8_LAS bf16x8*)(lds + PG8_SB(b, h) + boff + n * 2048 + k * 1024); } while (0)
; #define PG8_MMA(ai, bj, At, Bt) do { __builtin_amdgcn_s_setprio(1); _Pragma("unroll") for (int m = 0; m < 4; ++m) _Pragma("unroll") for (int n = 0; n < 2; ++n) _Pragma("unroll") for (int k = 0; k < 2; ++k) \
;         acc[ai][bj][m][n] = __builtin_amdgcn_mfma_f32_16x16x32_bf16(Bt[n][k], At[m][k], acc[ai][bj][m][n], 0, 0, 0); __builtin_amdgcn_s_setprio(0); } while (0)
; #define PG8_WAIT_V(n) asm volatile("s_waitcnt vmcnt(" #n ")" ::: "memory")
; #define PG8_BAR __builtin_amdgcn_s_barrier()
; template <class Epi, class Sched, bool ALIGN_EPI = false, bool SP2 = false>
; __device__ __forceinline__ void gemm_phase(PG8_LAS unsigned char* lds, const Gemm g, const Sched& S, const Epi& E) {
;     ...
;         for (int t = 0; t < nt; t += 2) {
;             const bool last = (t == nt - 2);
;             const char* a1 = cA + (size_t)(t + 1) * kstep;
;             const char* a2 = last ? nA : cA + (size_t)(t + 2) * kstep; const char* b2 = last ? nB : cB + (size_t)(t + 2) * kstep;
;             const char* a3 = a2 + kstep; const char* b3 = b2 + kstep;
;             if (last && has_next) S.a_ready(nxt);
;             if constexpr (SP2) {
;             PG8_LDB(B0, 0, 0); PG8_LDB(B1, 0, 1); PG8_SCHED; PG8_LDA(At, 0, 0); PG8_STAGE(PG8_SA(1, 1), a1 + hstep, voffA);
;             PG8_WAIT_V(8); PG8_WAIT_L(0); PG8_BAR; PG8_MMA(0, 0, At, B0); PG8_MMA(0, 1, At, B1); PG8_BAR; PG8_SCHED;
;             PG8_LDA(At, 0, 1); PG8_STAGE(PG8_SB(0, 0), b2, voffB); PG8_STAGE(PG8_SB(0, 1), b2 + hstep, voffB); PG8_STAGE(PG8_SA(0, 0), a2, voffA);
;             PG8_WAIT_V(8); PG8_WAIT_L(0); PG8_BAR; PG8_MMA(1, 0, At, B0); PG8_MMA(1, 1, At, B1); PG8_BAR; PG8_SCHED;
.LBB0_800:
	s_add_u32 s10, s8, 0xfffc0080
	s_addc_u32 s11, s9, -1
	s_add_i32 s67, 0, 0x10000
	s_cmp_eq_u32 s66, 12
	s_cselect_b32 s29, s5, s11
	s_cselect_b32 s28, s7, s10
	v_add_u32_e32 v0, s67, v156
	s_cselect_b32 s11, s27, s61
	s_cselect_b32 s10, s35, s60
	s_add_i32 s70, 0, 0x14000
	ds_read_b128 v[142:145], v0
	ds_read_b128 v[146:149], v0 offset:1024
	ds_read_b128 v[150:153], v0 offset:2048
	ds_read_b128 v[158:161], v0 offset:3072
	v_add_u32_e32 v0, s70, v156
	ds_read_b128 v[162:165], v0
	ds_read_b128 v[166:169], v0 offset:1024
	ds_read_b128 v[170:173], v0 offset:2048
	ds_read_b128 v[174:177], v0 offset:3072
	v_lshl_add_u64 v[154:155], s[8:9], 0, v[138:139]
	s_add_i32 m0, s48, 0xc000
	ds_read_b128 v[178:181], v157
	ds_read_b128 v[182:185], v157 offset:1024
	ds_read_b128 v[186:189], v157 offset:2048
	ds_read_b128 v[190:193], v157 offset:3072
	ds_read_b128 v[218:221], v157 offset:4096
	ds_read_b128 v[222:225], v157 offset:5120
	ds_read_b128 v[226:229], v157 offset:6144
	ds_read_b128 v[230:233], v157 offset:7168
	global_load_lds_dwordx4 v[154:155], off
	v_lshl_add_u64 v[154:155], s[8:9], 0, v[140:141]
	s_add_i32 m0, s48, 0xe000
	s_nop 0
	global_load_lds_dwordx4 v[154:155], off
	s_waitcnt vmcnt(8)
	s_waitcnt lgkmcnt(0)
	s_barrier
	s_setprio 1
	s_waitcnt lgkmcnt(0)
	v_mfma_f32_16x16x32_bf16 v[126:129], v[142:145], v[178:181], v[126:129]
	v_mfma_f32_16x16x32_bf16 v[122:125], v[150:153], v[178:181], v[122:125]
	v_mfma_f32_16x16x32_bf16 v[110:113], v[142:145], v[186:189], v[110:113]
	v_mfma_f32_16x16x32_bf16 v[106:109], v[150:153], v[186:189], v[106:109]
	v_mfma_f32_16x16x32_bf16 v[94:97], v[142:145], v[218:221], v[94:97]
	v_mfma_f32_16x16x32_bf16 v[90:93], v[150:153], v[218:221], v[90:93]
	v_mfma_f32_16x16x32_bf16 v[78:81], v[142:145], v[226:229], v[78:81]
	v_mfma_f32_16x16x32_bf16 v[74:77], v[150:153], v[226:229], v[74:77]
	v_mfma_f32_16x16x32_bf16 v[126:129], v[146:149], v[182:185], v[126:129]
	v_mfma_f32_16x16x32_bf16 v[122:125], v[158:161], v[182:185], v[122:125]
	v_mfma_f32_16x16x32_bf16 v[110:113], v[146:149], v[190:193], v[110:113]
	v_mfma_f32_16x16x32_bf16 v[106:109], v[158:161], v[190:193], v[106:109]
	v_mfma_f32_16x16x32_bf16 v[94:97], v[146:149], v[222:225], v[94:97]
	v_mfma_f32_16x16x32_bf16 v[90:93], v[158:161], v[222:225], v[90:93]
	v_mfma_f32_16x16x32_bf16 v[78:81], v[146:149], v[230:233], v[78:81]
	v_mfma_f32_16x16x32_bf16 v[74:77], v[158:161], v[230:233], v[74:77]
	s_setprio 0
	s_setprio 1
	v_mfma_f32_16x16x32_bf16 v[118:121], v[162:165], v[178:181], v[118:121]
	v_mfma_f32_16x16x32_bf16 v[114:117], v[170:173], v[178:181], v[114:117]
	v_mfma_f32_16x16x32_bf16 v[102:105], v[162:165], v[186:189], v[102:105]
	v_mfma_f32_16x16x32_bf16 v[98:101], v[170:173], v[186:189], v[98:101]
	v_mfma_f32_16x16x32_bf16 v[86:89], v[162:165], v[218:221], v[86:89]
	v_mfma_f32_16x16x32_bf16 v[82:85], v[170:173], v[218:221], v[82:85]
	v_mfma_f32_16x16x32_bf16 v[70:73], v[162:165], v[226:229], v[70:73]
	v_mfma_f32_16x16x32_bf16 v[66:69], v[170:173], v[226:229], v[66:69]
	v_mfma_f32_16x16x32_bf16 v[118:121], v[166:169], v[182:185], v[118:121]
	v_mfma_f32_16x16x32_bf16 v[114:117], v[174:177], v[182:185], v[114:117]
	v_mfma_f32_16x16x32_bf16 v[102:105], v[166:169], v[190:193], v[102:105]
	v_mfma_f32_16x16x32_bf16 v[98:101], v[174:177], v[190:193], v[98:101]
	v_mfma_f32_16x16x32_bf16 v[86:89], v[166:169], v[222:225], v[86:89]
	v_mfma_f32_16x16x32_bf16 v[82:85], v[174:177], v[222:225], v[82:85]
	v_mfma_f32_16x16x32_bf16 v[70:73], v[166:169], v[230:233], v[70:73]
	v_mfma_f32_16x16x32_bf16 v[66:69], v[174:177], v[230:233], v[66:69]
	s_setprio 0
	s_barrier
	s_add_i32 s67, s67, s47
	v_lshl_add_u64 v[154:155], s[10:11], 0, v[132:133]
	s_mov_b32 m0, s67
	ds_read_b128 v[178:181], v157 offset:16384
	ds_read_b128 v[182:185], v157 offset:17408
	ds_read_b128 v[186:189], v157 offset:18432
	ds_read_b128 v[190:193], v157 offset:19456
	ds_read_b128 v[218:221], v157 offset:20480
	ds_read_b128 v[222:225], v157 offset:21504
	ds_read_b128 v[226:229], v157 offset:22528
	ds_read_b128 v[230:233], v157 offset:23552
	global_load_lds_dwordx4 v[154:155], off
	s_add_i32 m0, s67, 0x2000
	s_add_u32 s68, s10, 0x40000
	v_lshl_add_u64 v[194:195], s[10:11], 0, v[136:137]
	s_addc_u32 s69, s11, 0
	s_add_i32 s67, s70, s47
	global_load_lds_dwordx4 v[194:195], off
	v_lshl_add_u64 v[196:197], s[68:69], 0, v[132:133]
	s_mov_b32 m0, s67
	v_lshl_add_u64 v[198:199], s[28:29], 0, v[134:135]
	global_load_lds_dwordx4 v[196:197], off
	v_lshl_add_u64 v[196:197], s[68:69], 0, v[136:137]
	s_add_i32 m0, s67, 0x2000
	s_nop 0
	global_load_lds_dwordx4 v[196:197], off
	v_lshl_add_u64 v[196:197], s[28:29], 0, v[130:131]
	s_mov_b32 m0, s48
	s_nop 0
	global_load_lds_dwordx4 v[196:197], off
	s_mov_b32 m0, s49
	s_nop 0
	global_load_lds_dwordx4 v[198:199], off
	s_waitcnt vmcnt(8)
	s_waitcnt lgkmcnt(0)
	s_barrier
; #define PG8_STAGE(bufoff, gbase, voff) do { _Pragma("unroll") for (int _i = 0; _i < 2; ++_i) \
;         __builtin_amdgcn_global_load_lds((const unsigned*)((const char*)(gbase) + (voff)[_i]), (PG8_LAS unsigned*)(lds + (bufoff) + ldsw + _i * 8192), 16, 0, 0); } while (0)
; #define PG8_LDA(dst, b, h) do { _Pragma("unroll") for (int m = 0; m < 4; ++m) _Pragma("unroll") for (int k = 0; k < 2; ++k) dst[m][k] = *(const PG8_LAS bf16x8*)(lds + PG8_SA(b, h) + aoff + m * 2048 + k * 1024); } while (0)
; #define PG8_LDB(dst, b, h) do { _Pragma("unroll") for (int n = 0; n < 2; ++n) _Pragma("unroll") for (int k = 0; k < 2; ++k) dst[n][k] = *(const PG8_LAS bf16x8*)(lds + PG8_SB(b, h) + boff + n * 2048 + k * 1024); } while (0)
; #define PG8_MMA(ai, bj, At, Bt) do { __builtin_amdgcn_s_setprio(1); _Pragma("unroll") for (int m = 0; m < 4; ++m) _Pragma("unroll") for (int n = 0; n < 2; ++n) _Pragma("unroll") for (int k = 0; k < 2; ++k) \
;         acc[ai][bj][m][n] = __builtin_amdgcn_mfma_f32_16x16x32_bf16(Bt[n][k], At[m][k], acc[ai][bj][m][n], 0, 0, 0); __builtin_amdgcn_s_setprio(0); } while (0)
; #define PG8_WAIT_V(n) asm volatile("s_waitcnt vmcnt(" #n ")" ::: "memory")
; #define PG8_WAIT_L(n) asm volatile("s_waitcnt lgkmcnt(" #n ")" ::: "memory")
; #define PG8_BAR __builtin_amdgcn_s_barrier()
; #define PG8_SCHED __builtin_amdgcn_sched_barrier(0)
; template <class Epi, class Sched, bool ALIGN_EPI = false, bool SP2 = false>
; __device__ __forceinline__ void gemm_phase(PG8_LAS unsigned char* lds, const Gemm g, const Sched& S, const Epi& E) {
;     ...
;             PG8_WAIT_V(8); PG8_WAIT_L(0); PG8_BAR; PG8_MMA(1, 0, At, B0); PG8_MMA(1, 1, At, B1); PG8_BAR; PG8_SCHED;
;             PG8_LDB(B0, 1, 0); PG8_LDB(B1, 1, 1); PG8_SCHED; PG8_LDA(At, 1, 0); PG8_STAGE(PG8_SA(0, 1), a2 + hstep, voffA);
;             PG8_WAIT_V(8); PG8_WAIT_L(0); PG8_BAR; PG8_MMA(0, 0, At, B0); PG8_MMA(0, 1, At, B1); PG8_BAR; PG8_SCHED;
	s_setprio 1
	s_waitcnt lgkmcnt(0)
	v_mfma_f32_16x16x32_bf16 v[62:65], v[142:145], v[178:181], v[62:65]
	v_mfma_f32_16x16x32_bf16 v[58:61], v[150:153], v[178:181], v[58:61]
	v_mfma_f32_16x16x32_bf16 v[46:49], v[142:145], v[186:189], v[46:49]
	v_mfma_f32_16x16x32_bf16 v[42:45], v[150:153], v[186:189], v[42:45]
	v_mfma_f32_16x16x32_bf16 v[30:33], v[142:145], v[218:221], v[30:33]
	v_mfma_f32_16x16x32_bf16 v[26:29], v[150:153], v[218:221], v[26:29]
	v_mfma_f32_16x16x32_bf16 v[14:17], v[142:145], v[226:229], v[14:17]
	v_mfma_f32_16x16x32_bf16 v[10:13], v[150:153], v[226:229], v[10:13]
	v_mfma_f32_16x16x32_bf16 v[62:65], v[146:149], v[182:185], v[62:65]
	v_mfma_f32_16x16x32_bf16 v[58:61], v[158:161], v[182:185], v[58:61]
	v_mfma_f32_16x16x32_bf16 v[46:49], v[146:149], v[190:193], v[46:49]
	v_mfma_f32_16x16x32_bf16 v[42:45], v[158:161], v[190:193], v[42:45]
	v_mfma_f32_16x16x32_bf16 v[30:33], v[146:149], v[222:225], v[30:33]
	v_mfma_f32_16x16x32_bf16 v[26:29], v[158:161], v[222:225], v[26:29]
	v_mfma_f32_16x16x32_bf16 v[14:17], v[146:149], v[230:233], v[14:17]
	v_mfma_f32_16x16x32_bf16 v[10:13], v[158:161], v[230:233], v[10:13]
	s_setprio 0
	s_setprio 1
	v_mfma_f32_16x16x32_bf16 v[54:57], v[162:165], v[178:181], v[54:57]
	v_mfma_f32_16x16x32_bf16 v[50:53], v[170:173], v[178:181], v[50:53]
	v_mfma_f32_16x16x32_bf16 v[38:41], v[162:165], v[186:189], v[38:41]
	v_mfma_f32_16x16x32_bf16 v[34:37], v[170:173], v[186:189], v[34:37]
	v_mfma_f32_16x16x32_bf16 v[22:25], v[162:165], v[218:221], v[22:25]
	v_mfma_f32_16x16x32_bf16 v[18:21], v[170:173], v[218:221], v[18:21]
	v_mfma_f32_16x16x32_bf16 v[6:9], v[162:165], v[226:229], v[6:9]
	v_mfma_f32_16x16x32_bf16 v[2:5], v[170:173], v[226:229], v[2:5]
	v_mfma_f32_16x16x32_bf16 v[54:57], v[166:169], v[182:185], v[54:57]
	v_mfma_f32_16x16x32_bf16 v[50:53], v[174:177], v[182:185], v[50:53]
	v_mfma_f32_16x16x32_bf16 v[38:41], v[166:169], v[190:193], v[38:41]
	v_mfma_f32_16x16x32_bf16 v[34:37], v[174:177], v[190:193], v[34:37]
	v_mfma_f32_16x16x32_bf16 v[22:25], v[166:169], v[222:225], v[22:25]
	v_mfma_f32_16x16x32_bf16 v[18:21], v[174:177], v[222:225], v[18:21]
	v_mfma_f32_16x16x32_bf16 v[6:9], v[166:169], v[230:233], v[6:9]
	v_mfma_f32_16x16x32_bf16 v[2:5], v[174:177], v[230:233], v[2:5]
	s_setprio 0
	s_barrier
	s_add_i32 s67, 0, 0x18000
	v_add_u32_e32 v0, s67, v156
	s_add_i32 s68, 0, 0x1c000
	ds_read_b128 v[142:145], v0
	ds_read_b128 v[146:149], v0 offset:1024
	ds_read_b128 v[150:153], v0 offset:2048
	ds_read_b128 v[158:161], v0 offset:3072
	v_add_u32_e32 v0, s68, v156
	ds_read_b128 v[162:165], v0
	ds_read_b128 v[166:169], v0 offset:1024
	ds_read_b128 v[170:173], v0 offset:2048
	ds_read_b128 v[174:177], v0 offset:3072
	s_add_u32 s28, s28, 0x40000
	s_addc_u32 s29, s29, 0
	s_mov_b32 m0, s50
	v_lshl_add_u64 v[202:203], s[28:29], 0, v[130:131]
	ds_read_b128 v[178:181], v157 offset:32768
	ds_read_b128 v[182:185], v157 offset:33792
	ds_read_b128 v[186:189], v157 offset:34816
	ds_read_b128 v[190:193], v157 offset:35840
	ds_read_b128 v[218:221], v157 offset:36864
	ds_read_b128 v[222:225], v157 offset:37888
	ds_read_b128 v[226:229], v157 offset:38912
	ds_read_b128 v[230:233], v157 offset:39936
	global_load_lds_dwordx4 v[202:203], off
	v_lshl_add_u64 v[202:203], s[28:29], 0, v[134:135]
	s_mov_b32 m0, s51
	s_nop 0
	global_load_lds_dwordx4 v[202:203], off
	s_waitcnt vmcnt(8)
	s_waitcnt lgkmcnt(0)
	s_barrier
	s_setprio 1
	s_waitcnt lgkmcnt(0)
	v_mfma_f32_16x16x32_bf16 v[126:129], v[142:145], v[178:181], v[126:129]
	v_mfma_f32_16x16x32_bf16 v[122:125], v[150:153], v[178:181], v[122:125]
	v_mfma_f32_16x16x32_bf16 v[110:113], v[142:145], v[186:189], v[110:113]
	v_mfma_f32_16x16x32_bf16 v[106:109], v[150:153], v[186:189], v[106:109]
	v_mfma_f32_16x16x32_bf16 v[94:97], v[142:145], v[218:221], v[94:97]
	v_mfma_f32_16x16x32_bf16 v[90:93], v[150:153], v[218:221], v[90:93]
	v_mfma_f32_16x16x32_bf16 v[78:81], v[142:145], v[226:229], v[78:81]
	v_mfma_f32_16x16x32_bf16 v[74:77], v[150:153], v[226:229], v[74:77]
	v_mfma_f32_16x16x32_bf16 v[126:129], v[146:149], v[182:185], v[126:129]
	v_mfma_f32_16x16x32_bf16 v[122:125], v[158:161], v[182:185], v[122:125]
	v_mfma_f32_16x16x32_bf16 v[110:113], v[146:149], v[190:193], v[110:113]
	v_mfma_f32_16x16x32_bf16 v[106:109], v[158:161], v[190:193], v[106:109]
	v_mfma_f32_16x16x32_bf16 v[94:97], v[146:149], v[222:225], v[94:97]
	v_mfma_f32_16x16x32_bf16 v[90:93], v[158:161], v[222:225], v[90:93]
	v_mfma_f32_16x16x32_bf16 v[78:81], v[146:149], v[230:233], v[78:81]
	v_mfma_f32_16x16x32_bf16 v[74:77], v[158:161], v[230:233], v[74:77]
	s_setprio 0
	s_setprio 1
	v_mfma_f32_16x16x32_bf16 v[118:121], v[162:165], v[178:181], v[118:121]
	v_mfma_f32_16x16x32_bf16 v[114:117], v[170:173], v[178:181], v[114:117]
	v_mfma_f32_16x16x32_bf16 v[102:105], v[162:165], v[186:189], v[102:105]
	v_mfma_f32_16x16x32_bf16 v[98:101], v[170:173], v[186:189], v[98:101]
	v_mfma_f32_16x16x32_bf16 v[86:89], v[162:165], v[218:221], v[86:89]
	v_mfma_f32_16x16x32_bf16 v[82:85], v[170:173], v[218:221], v[82:85]
	v_mfma_f32_16x16x32_bf16 v[70:73], v[162:165], v[226:229], v[70:73]
	v_mfma_f32_16x16x32_bf16 v[66:69], v[170:173], v[226:229], v[66:69]
	v_mfma_f32_16x16x32_bf16 v[118:121], v[166:169], v[182:185], v[118:121]
	v_mfma_f32_16x16x32_bf16 v[114:117], v[174:177], v[182:185], v[114:117]
	v_mfma_f32_16x16x32_bf16 v[102:105], v[166:169], v[190:193], v[102:105]
	v_mfma_f32_16x16x32_bf16 v[98:101], v[174:177], v[190:193], v[98:101]
	v_mfma_f32_16x16x32_bf16 v[86:89], v[166:169], v[222:225], v[86:89]
	v_mfma_f32_16x16x32_bf16 v[82:85], v[174:177], v[222:225], v[82:85]
	v_mfma_f32_16x16x32_bf16 v[70:73], v[166:169], v[230:233], v[70:73]
	v_mfma_f32_16x16x32_bf16 v[66:69], v[174:177], v[230:233], v[66:69]
	s_setprio 0
	s_barrier
; #define PG8_STAGE(bufoff, gbase, voff) do { _Pragma("unroll") for (int _i = 0; _i < 2; ++_i) \
;         __builtin_amdgcn_global_load_lds((const unsigned*)((const char*)(gbase) + (voff)[_i]), (PG8_LAS unsigned*)(lds + (bufoff) + ldsw + _i * 8192), 16, 0, 0); } while (0)
; #define PG8_LDA(dst, b, h) do { _Pragma("unroll") for (int m = 0; m < 4; ++m) _Pragma("unroll") for (int k = 0; k < 2; ++k) dst[m][k] = *(const PG8_LAS bf16x8*)(lds + PG8_SA(b, h) + aoff + m * 2048 + k * 1024); } while (0)
; #define PG8_MMA(ai, bj, At, Bt) do { __builtin_amdgcn_s_setprio(1); _Pragma("unroll") for (int m = 0; m < 4; ++m) _Pragma("unroll") for (int n = 0; n < 2; ++n) _Pragma("unroll") for (int k = 0; k < 2; ++k) \
;         acc[ai][bj][m][n] = __builtin_amdgcn_mfma_f32_16x16x32_bf16(Bt[n][k], At[m][k], acc[ai][bj][m][n], 0, 0, 0); __builtin_amdgcn_s_setprio(0); } while (0)
; #define PG8_WAIT_V(n) asm volatile("s_waitcnt vmcnt(" #n ")" ::: "memory")
; #define PG8_WAIT_L(n) asm volatile("s_waitcnt lgkmcnt(" #n ")" ::: "memory")
; #define PG8_BAR __builtin_amdgcn_s_barrier()
; #define PG8_SCHED __builtin_amdgcn_sched_barrier(0)
; template <class Epi, class Sched, bool ALIGN_EPI = false, bool SP2 = false>
; __device__ __forceinline__ void gemm_phase(PG8_LAS unsigned char* lds, const Gemm g, const Sched& S, const Epi& E) {
;     ...
;         for (int t = 0; t < nt; t += 2) {
;     ...
;             PG8_LDA(At, 1, 1); PG8_STAGE(PG8_SB(1, 0), b3, voffB); PG8_STAGE(PG8_SB(1, 1), b3 + hstep, voffB); PG8_STAGE(PG8_SA(1, 0), a3, voffA);
;             PG8_WAIT_V(8); PG8_WAIT_L(0); PG8_BAR; PG8_MMA(1, 0, At, B0); PG8_MMA(1, 1, At, B1); PG8_BAR; PG8_SCHED;
	s_add_i32 s28, s67, s47
	v_lshl_add_u64 v[154:155], v[154:155], 0, s[84:85]
	s_mov_b32 m0, s28
	ds_read_b128 v[178:181], v157 offset:49152
	ds_read_b128 v[182:185], v157 offset:50176
	ds_read_b128 v[186:189], v157 offset:51200
	ds_read_b128 v[190:193], v157 offset:52224
	ds_read_b128 v[218:221], v157 offset:53248
	ds_read_b128 v[222:225], v157 offset:54272
	ds_read_b128 v[226:229], v157 offset:55296
	ds_read_b128 v[230:233], v157 offset:56320
	global_load_lds_dwordx4 v[154:155], off
	s_add_i32 m0, s28, 0x2000
	s_add_u32 s10, s10, 0x40080
	v_lshl_add_u64 v[154:155], v[194:195], 0, s[84:85]
	s_addc_u32 s11, s11, 0
	s_add_i32 s28, s68, s47
	global_load_lds_dwordx4 v[154:155], off
	v_lshl_add_u64 v[154:155], s[10:11], 0, v[132:133]
	s_mov_b32 m0, s28
	s_nop 0
	global_load_lds_dwordx4 v[154:155], off
	v_lshl_add_u64 v[154:155], s[10:11], 0, v[136:137]
	s_add_i32 m0, s28, 0x2000
	s_nop 0
	global_load_lds_dwordx4 v[154:155], off
	v_lshl_add_u64 v[154:155], v[196:197], 0, s[84:85]
	s_mov_b32 m0, s63
	s_nop 0
	global_load_lds_dwordx4 v[154:155], off
	v_lshl_add_u64 v[154:155], v[198:199], 0, s[84:85]
	s_mov_b32 m0, s64
	s_nop 0
	global_load_lds_dwordx4 v[154:155], off
	s_waitcnt vmcnt(8)
	s_waitcnt lgkmcnt(0)
	s_barrier
	s_setprio 1
	s_waitcnt lgkmcnt(0)
	v_mfma_f32_16x16x32_bf16 v[62:65], v[142:145], v[178:181], v[62:65]
	v_mfma_f32_16x16x32_bf16 v[58:61], v[150:153], v[178:181], v[58:61]
	v_mfma_f32_16x16x32_bf16 v[46:49], v[142:145], v[186:189], v[46:49]
	v_mfma_f32_16x16x32_bf16 v[42:45], v[150:153], v[186:189], v[42:45]
	v_mfma_f32_16x16x32_bf16 v[30:33], v[142:145], v[218:221], v[30:33]
	v_mfma_f32_16x16x32_bf16 v[26:29], v[150:153], v[218:221], v[26:29]
	v_mfma_f32_16x16x32_bf16 v[14:17], v[142:145], v[226:229], v[14:17]
	v_mfma_f32_16x16x32_bf16 v[10:13], v[150:153], v[226:229], v[10:13]
	v_mfma_f32_16x16x32_bf16 v[62:65], v[146:149], v[182:185], v[62:65]
	v_mfma_f32_16x16x32_bf16 v[58:61], v[158:161], v[182:185], v[58:61]
	v_mfma_f32_16x16x32_bf16 v[46:49], v[146:149], v[190:193], v[46:49]
	v_mfma_f32_16x16x32_bf16 v[42:45], v[158:161], v[190:193], v[42:45]
	v_mfma_f32_16x16x32_bf16 v[30:33], v[146:149], v[222:225], v[30:33]
	v_mfma_f32_16x16x32_bf16 v[26:29], v[158:161], v[222:225], v[26:29]
	v_mfma_f32_16x16x32_bf16 v[14:17], v[146:149], v[230:233], v[14:17]
	v_mfma_f32_16x16x32_bf16 v[10:13], v[158:161], v[230:233], v[10:13]
	s_setprio 0
	s_setprio 1
	v_mfma_f32_16x16x32_bf16 v[54:57], v[162:165], v[178:181], v[54:57]
	v_mfma_f32_16x16x32_bf16 v[50:53], v[170:173], v[178:181], v[50:53]
	v_mfma_f32_16x16x32_bf16 v[38:41], v[162:165], v[186:189], v[38:41]
	v_mfma_f32_16x16x32_bf16 v[34:37], v[170:173], v[186:189], v[34:37]
	v_mfma_f32_16x16x32_bf16 v[22:25], v[162:165], v[218:221], v[22:25]
	v_mfma_f32_16x16x32_bf16 v[18:21], v[170:173], v[218:221], v[18:21]
	v_mfma_f32_16x16x32_bf16 v[6:9], v[162:165], v[226:229], v[6:9]
	v_mfma_f32_16x16x32_bf16 v[2:5], v[170:173], v[226:229], v[2:5]
	v_mfma_f32_16x16x32_bf16 v[54:57], v[166:169], v[182:185], v[54:57]
	v_mfma_f32_16x16x32_bf16 v[50:53], v[174:177], v[182:185], v[50:53]
	v_mfma_f32_16x16x32_bf16 v[38:41], v[166:169], v[190:193], v[38:41]
	v_mfma_f32_16x16x32_bf16 v[34:37], v[174:177], v[190:193], v[34:37]
	v_mfma_f32_16x16x32_bf16 v[22:25], v[166:169], v[222:225], v[22:25]
	v_mfma_f32_16x16x32_bf16 v[18:21], v[174:177], v[222:225], v[18:21]
	v_mfma_f32_16x16x32_bf16 v[6:9], v[166:169], v[230:233], v[6:9]
	v_mfma_f32_16x16x32_bf16 v[2:5], v[174:177], v[230:233], v[2:5]
	s_setprio 0
	s_add_i32 s66, s66, 2
	s_add_u32 s8, s8, 0x100
	s_addc_u32 s9, s9, 0
	s_add_u32 s60, s60, 0x100
	s_addc_u32 s61, s61, 0
	s_cmp_gt_u32 s66, 13
	s_barrier
	s_cbranch_scc0 .LBB0_800
	s_and_b64 vcc, exec, s[24:25]
	s_cbranch_vccz .LBB0_803
	s_barrier

; #define PG8_STAGE(bufoff, gbase, voff) do { _Pragma("unroll") for (int _i = 0; _i < 2; ++_i) \
;         __builtin_amdgcn_global_load_lds((const unsigned*)((const char*)(gbase) + (voff)[_i]), (PG8_LAS unsigned*)(lds + (bufoff) + ldsw + _i * 8192), 16, 0, 0); } while (0)
; #define PG8_LDA(dst, b, h) do { _Pragma("unroll") for (int m = 0; m < 4; ++m) _Pragma("unroll") for (int k = 0; k < 2; ++k) dst[m][k] = *(const PG8_LAS bf16x8*)(lds + PG8_SA(b, h) + aoff + m * 2048 + k * 1024); } while (0)
; #define PG8_LDB(dst, b, h) do { _Pragma("unroll") for (int n = 0; n < 2; ++n) _Pragma("unroll") for (int k = 0; k < 2; ++k) dst[n][k] = *(const PG8_LAS bf16x8*)(lds + PG8_SB(b, h) + boff + n * 2048 + k * 1024); } while (0)
; #define PG8_MMA(ai, bj, At, Bt) do { __builtin_amdgcn_s_setprio(1); _Pragma("unroll") for (int m = 0; m < 4; ++m) _Pragma("unroll") for (int n = 0; n < 2; ++n) _Pragma("unroll") for (int k = 0; k < 2; ++k) \
;         acc[ai][bj][m][n] = __builtin_amdgcn_mfma_f32_16x16x32_bf16(Bt[n][k], At[m][k], acc[ai][bj][m][n], 0, 0, 0); __builtin_amdgcn_s_setprio(0); } while (0)
; #define PG8_WAIT_V(n) asm volatile("s_waitcnt vmcnt(" #n ")" ::: "memory")
; #define PG8_BAR __builtin_amdgcn_s_barrier()
; template <class Epi, class Sched, bool ALIGN_EPI = false, bool SP2 = false>
; __device__ __forceinline__ void gemm_phase(PG8_LAS unsigned char* lds, const Gemm g, const Sched& S, const Epi& E) {
;     ...
;         for (int t = 0; t < nt; t += 2) {
;             const bool last = (t == nt - 2);
;             const char* a1 = cA + (size_t)(t + 1) * kstep;
;             const char* a2 = last ? nA : cA + (size_t)(t + 2) * kstep; const char* b2 = last ? nB : cB + (size_t)(t + 2) * kstep;
;             const char* a3 = a2 + kstep; const char* b3 = b2 + kstep;
;             if (last && has_next) S.a_ready(nxt);
;             if constexpr (SP2) {
;             PG8_LDB(B0, 0, 0); PG8_LDB(B1, 0, 1); PG8_SCHED; PG8_LDA(At, 0, 0); PG8_STAGE(PG8_SA(1, 1), a1 + hstep, voffA);
;             PG8_WAIT_V(8); PG8_WAIT_L(0); PG8_BAR; PG8_MMA(0, 0, At, B0); PG8_MMA(0, 1, At, B1); PG8_BAR; PG8_SCHED;
;             PG8_LDA(At, 0, 1); PG8_STAGE(PG8_SB(0, 0), b2, voffB); PG8_STAGE(PG8_SB(0, 1), b2 + hstep, voffB); PG8_STAGE(PG8_SA(0, 0), a2, voffA);
;             PG8_WAIT_V(8); PG8_WAIT_L(0); PG8_BAR; PG8_MMA(1, 0, At, B0); PG8_MMA(1, 1, At, B1); PG8_BAR; PG8_SCHED;
.LBB0_1557:
	s_add_u32 s24, s18, 0xfff80080
	s_addc_u32 s25, s19, -1
	s_add_i32 s62, 0, 0x10000
	s_cmp_eq_u32 s61, 28
	s_cselect_b32 s27, s13, s25
	s_cselect_b32 s26, s57, s24
	v_add_u32_e32 v140, s62, v142
	s_cselect_b32 s25, s11, s60
	s_cselect_b32 s24, s58, s59
	s_add_i32 s64, 0, 0x14000
	ds_read_b128 v[144:147], v140
	ds_read_b128 v[148:151], v140 offset:1024
	ds_read_b128 v[152:155], v140 offset:2048
	ds_read_b128 v[156:159], v140 offset:3072
	v_add_u32_e32 v140, s64, v142
	ds_read_b128 v[160:163], v140
	ds_read_b128 v[164:167], v140 offset:1024
	ds_read_b128 v[168:171], v140 offset:2048
	ds_read_b128 v[172:175], v140 offset:3072
	v_lshl_add_u64 v[140:141], s[18:19], 0, v[136:137]
	s_add_i32 m0, s46, 0xc000
	ds_read_b128 v[176:179], v143
	ds_read_b128 v[180:183], v143 offset:1024
	ds_read_b128 v[184:187], v143 offset:2048
	ds_read_b128 v[188:191], v143 offset:3072
	ds_read_b128 v[192:195], v143 offset:4096
	ds_read_b128 v[196:199], v143 offset:5120
	ds_read_b128 v[202:205], v143 offset:6144
	ds_read_b128 v[206:209], v143 offset:7168
	global_load_lds_dwordx4 v[140:141], off
	v_lshl_add_u64 v[140:141], s[18:19], 0, v[138:139]
	s_add_i32 m0, s46, 0xe000
	s_nop 0
	global_load_lds_dwordx4 v[140:141], off
	s_waitcnt vmcnt(8)
	s_waitcnt lgkmcnt(0)
	s_barrier
	s_setprio 1
	s_waitcnt lgkmcnt(0)
	v_mfma_f32_16x16x32_bf16 v[126:129], v[144:147], v[176:179], v[126:129]
	v_mfma_f32_16x16x32_bf16 v[122:125], v[152:155], v[176:179], v[122:125]
	v_mfma_f32_16x16x32_bf16 v[118:121], v[144:147], v[184:187], v[118:121]
	v_mfma_f32_16x16x32_bf16 v[110:113], v[152:155], v[184:187], v[110:113]
	v_mfma_f32_16x16x32_bf16 v[102:105], v[144:147], v[192:195], v[102:105]
	v_mfma_f32_16x16x32_bf16 v[94:97], v[152:155], v[192:195], v[94:97]
	v_mfma_f32_16x16x32_bf16 v[86:89], v[144:147], v[202:205], v[86:89]
	v_mfma_f32_16x16x32_bf16 v[78:81], v[152:155], v[202:205], v[78:81]
	v_mfma_f32_16x16x32_bf16 v[126:129], v[148:151], v[180:183], v[126:129]
	v_mfma_f32_16x16x32_bf16 v[122:125], v[156:159], v[180:183], v[122:125]
	v_mfma_f32_16x16x32_bf16 v[118:121], v[148:151], v[188:191], v[118:121]
	v_mfma_f32_16x16x32_bf16 v[110:113], v[156:159], v[188:191], v[110:113]
	v_mfma_f32_16x16x32_bf16 v[102:105], v[148:151], v[196:199], v[102:105]
	v_mfma_f32_16x16x32_bf16 v[94:97], v[156:159], v[196:199], v[94:97]
	v_mfma_f32_16x16x32_bf16 v[86:89], v[148:151], v[206:209], v[86:89]
	v_mfma_f32_16x16x32_bf16 v[78:81], v[156:159], v[206:209], v[78:81]
	s_setprio 0
	s_setprio 1
	v_mfma_f32_16x16x32_bf16 v[114:117], v[160:163], v[176:179], v[114:117]
	v_mfma_f32_16x16x32_bf16 v[106:109], v[168:171], v[176:179], v[106:109]
	v_mfma_f32_16x16x32_bf16 v[98:101], v[160:163], v[184:187], v[98:101]
	v_mfma_f32_16x16x32_bf16 v[90:93], v[168:171], v[184:187], v[90:93]
	v_mfma_f32_16x16x32_bf16 v[82:85], v[160:163], v[192:195], v[82:85]
	v_mfma_f32_16x16x32_bf16 v[74:77], v[168:171], v[192:195], v[74:77]
	v_mfma_f32_16x16x32_bf16 v[70:73], v[160:163], v[202:205], v[70:73]
	v_mfma_f32_16x16x32_bf16 v[66:69], v[168:171], v[202:205], v[66:69]
	v_mfma_f32_16x16x32_bf16 v[114:117], v[164:167], v[180:183], v[114:117]
	v_mfma_f32_16x16x32_bf16 v[106:109], v[172:175], v[180:183], v[106:109]
	v_mfma_f32_16x16x32_bf16 v[98:101], v[164:167], v[188:191], v[98:101]
	v_mfma_f32_16x16x32_bf16 v[90:93], v[172:175], v[188:191], v[90:93]
	v_mfma_f32_16x16x32_bf16 v[82:85], v[164:167], v[196:199], v[82:85]
	v_mfma_f32_16x16x32_bf16 v[74:77], v[172:175], v[196:199], v[74:77]
	v_mfma_f32_16x16x32_bf16 v[70:73], v[164:167], v[206:209], v[70:73]
	v_mfma_f32_16x16x32_bf16 v[66:69], v[172:175], v[206:209], v[66:69]
	s_setprio 0
	s_barrier
	s_add_i32 s62, s62, s37
	v_lshl_add_u64 v[140:141], s[24:25], 0, v[0:1]
	s_mov_b32 m0, s62
	ds_read_b128 v[176:179], v143 offset:16384
	ds_read_b128 v[180:183], v143 offset:17408
	ds_read_b128 v[184:187], v143 offset:18432
	ds_read_b128 v[188:191], v143 offset:19456
	ds_read_b128 v[192:195], v143 offset:20480
	ds_read_b128 v[196:199], v143 offset:21504
	ds_read_b128 v[202:205], v143 offset:22528
	ds_read_b128 v[206:209], v143 offset:23552
	global_load_lds_dwordx4 v[140:141], off
	s_add_i32 m0, s62, 0x2000
	s_add_u32 s62, s24, 0x80000
	v_lshl_add_u64 v[210:211], s[24:25], 0, v[130:131]
	s_addc_u32 s63, s25, 0
	s_add_i32 s64, s64, s37
	global_load_lds_dwordx4 v[210:211], off
	v_lshl_add_u64 v[212:213], s[62:63], 0, v[0:1]
	s_mov_b32 m0, s64
	v_lshl_add_u64 v[218:219], s[26:27], 0, v[132:133]
	global_load_lds_dwordx4 v[212:213], off
	v_lshl_add_u64 v[212:213], s[62:63], 0, v[130:131]
	s_add_i32 m0, s64, 0x2000
	s_nop 0
	global_load_lds_dwordx4 v[212:213], off
	v_lshl_add_u64 v[212:213], s[26:27], 0, v[134:135]
	s_mov_b32 m0, s46
	s_nop 0
	global_load_lds_dwordx4 v[212:213], off
	s_mov_b32 m0, s47
	s_nop 0
	global_load_lds_dwordx4 v[218:219], off
	s_waitcnt vmcnt(8)
	s_waitcnt lgkmcnt(0)
	s_barrier
; #define PG8_STAGE(bufoff, gbase, voff) do { _Pragma("unroll") for (int _i = 0; _i < 2; ++_i) \
;         __builtin_amdgcn_global_load_lds((const unsigned*)((const char*)(gbase) + (voff)[_i]), (PG8_LAS unsigned*)(lds + (bufoff) + ldsw + _i * 8192), 16, 0, 0); } while (0)
; #define PG8_LDA(dst, b, h) do { _Pragma("unroll") for (int m = 0; m < 4; ++m) _Pragma("unroll") for (int k = 0; k < 2; ++k) dst[m][k] = *(const PG8_LAS bf16x8*)(lds + PG8_SA(b, h) + aoff + m * 2048 + k * 1024); } while (0)
; #define PG8_LDB(dst, b, h) do { _Pragma("unroll") for (int n = 0; n < 2; ++n) _Pragma("unroll") for (int k = 0; k < 2; ++k) dst[n][k] = *(const PG8_LAS bf16x8*)(lds + PG8_SB(b, h) + boff + n * 2048 + k * 1024); } while (0)
; #define PG8_MMA(ai, bj, At, Bt) do { __builtin_amdgcn_s_setprio(1); _Pragma("unroll") for (int m = 0; m < 4; ++m) _Pragma("unroll") for (int n = 0; n < 2; ++n) _Pragma("unroll") for (int k = 0; k < 2; ++k) \
;         acc[ai][bj][m][n] = __builtin_amdgcn_mfma_f32_16x16x32_bf16(Bt[n][k], At[m][k], acc[ai][bj][m][n], 0, 0, 0); __builtin_amdgcn_s_setprio(0); } while (0)
; #define PG8_WAIT_V(n) asm volatile("s_waitcnt vmcnt(" #n ")" ::: "memory")
; #define PG8_WAIT_L(n) asm volatile("s_waitcnt lgkmcnt(" #n ")" ::: "memory")
; #define PG8_BAR __builtin_amdgcn_s_barrier()
; #define PG8_SCHED __builtin_amdgcn_sched_barrier(0)
; template <class Epi, class Sched, bool ALIGN_EPI = false, bool SP2 = false>
; __device__ __forceinline__ void gemm_phase(PG8_LAS unsigned char* lds, const Gemm g, const Sched& S, const Epi& E) {
;     ...
;             PG8_WAIT_V(8); PG8_WAIT_L(0); PG8_BAR; PG8_MMA(1, 0, At, B0); PG8_MMA(1, 1, At, B1); PG8_BAR; PG8_SCHED;
;             PG8_LDB(B0, 1, 0); PG8_LDB(B1, 1, 1); PG8_SCHED; PG8_LDA(At, 1, 0); PG8_STAGE(PG8_SA(0, 1), a2 + hstep, voffA);
;             PG8_WAIT_V(8); PG8_WAIT_L(0); PG8_BAR; PG8_MMA(0, 0, At, B0); PG8_MMA(0, 1, At, B1); PG8_BAR; PG8_SCHED;
	s_setprio 1
	s_waitcnt lgkmcnt(0)
	v_mfma_f32_16x16x32_bf16 v[62:65], v[144:147], v[176:179], v[62:65]
	v_mfma_f32_16x16x32_bf16 v[58:61], v[152:155], v[176:179], v[58:61]
	v_mfma_f32_16x16x32_bf16 v[54:57], v[144:147], v[184:187], v[54:57]
	v_mfma_f32_16x16x32_bf16 v[46:49], v[152:155], v[184:187], v[46:49]
	v_mfma_f32_16x16x32_bf16 v[38:41], v[144:147], v[192:195], v[38:41]
	v_mfma_f32_16x16x32_bf16 v[30:33], v[152:155], v[192:195], v[30:33]
	v_mfma_f32_16x16x32_bf16 v[22:25], v[144:147], v[202:205], v[22:25]
	v_mfma_f32_16x16x32_bf16 v[14:17], v[152:155], v[202:205], v[14:17]
	v_mfma_f32_16x16x32_bf16 v[62:65], v[148:151], v[180:183], v[62:65]
	v_mfma_f32_16x16x32_bf16 v[58:61], v[156:159], v[180:183], v[58:61]
	v_mfma_f32_16x16x32_bf16 v[54:57], v[148:151], v[188:191], v[54:57]
	v_mfma_f32_16x16x32_bf16 v[46:49], v[156:159], v[188:191], v[46:49]
	v_mfma_f32_16x16x32_bf16 v[38:41], v[148:151], v[196:199], v[38:41]
	v_mfma_f32_16x16x32_bf16 v[30:33], v[156:159], v[196:199], v[30:33]
	v_mfma_f32_16x16x32_bf16 v[22:25], v[148:151], v[206:209], v[22:25]
	v_mfma_f32_16x16x32_bf16 v[14:17], v[156:159], v[206:209], v[14:17]
	s_setprio 0
	s_setprio 1
	v_mfma_f32_16x16x32_bf16 v[50:53], v[160:163], v[176:179], v[50:53]
	v_mfma_f32_16x16x32_bf16 v[42:45], v[168:171], v[176:179], v[42:45]
	v_mfma_f32_16x16x32_bf16 v[34:37], v[160:163], v[184:187], v[34:37]
	v_mfma_f32_16x16x32_bf16 v[26:29], v[168:171], v[184:187], v[26:29]
	v_mfma_f32_16x16x32_bf16 v[18:21], v[160:163], v[192:195], v[18:21]
	v_mfma_f32_16x16x32_bf16 v[10:13], v[168:171], v[192:195], v[10:13]
	v_mfma_f32_16x16x32_bf16 v[6:9], v[160:163], v[202:205], v[6:9]
	v_mfma_f32_16x16x32_bf16 v[2:5], v[168:171], v[202:205], v[2:5]
	v_mfma_f32_16x16x32_bf16 v[50:53], v[164:167], v[180:183], v[50:53]
	v_mfma_f32_16x16x32_bf16 v[42:45], v[172:175], v[180:183], v[42:45]
	v_mfma_f32_16x16x32_bf16 v[34:37], v[164:167], v[188:191], v[34:37]
	v_mfma_f32_16x16x32_bf16 v[26:29], v[172:175], v[188:191], v[26:29]
	v_mfma_f32_16x16x32_bf16 v[18:21], v[164:167], v[196:199], v[18:21]
	v_mfma_f32_16x16x32_bf16 v[10:13], v[172:175], v[196:199], v[10:13]
	v_mfma_f32_16x16x32_bf16 v[6:9], v[164:167], v[206:209], v[6:9]
	v_mfma_f32_16x16x32_bf16 v[2:5], v[172:175], v[206:209], v[2:5]
	s_setprio 0
	s_barrier
	s_add_i32 s62, 0, 0x18000
	s_add_i32 s63, 0, 0x1c000
	v_add_u32_e32 v156, s62, v142
	v_add_u32_e32 v172, s63, v142
	ds_read_b128 v[144:147], v156
	ds_read_b128 v[148:151], v156 offset:1024
	ds_read_b128 v[152:155], v156 offset:2048
	ds_read_b128 v[156:159], v156 offset:3072
	ds_read_b128 v[160:163], v172
	ds_read_b128 v[164:167], v172 offset:1024
	ds_read_b128 v[168:171], v172 offset:2048
	ds_read_b128 v[172:175], v172 offset:3072
	s_add_u32 s26, s26, 0x80000
	s_addc_u32 s27, s27, 0
	s_mov_b32 m0, s48
	v_lshl_add_u64 v[220:221], s[26:27], 0, v[134:135]
	ds_read_b128 v[176:179], v143 offset:32768
	ds_read_b128 v[180:183], v143 offset:33792
	ds_read_b128 v[184:187], v143 offset:34816
	ds_read_b128 v[188:191], v143 offset:35840
	ds_read_b128 v[192:195], v143 offset:36864
	ds_read_b128 v[196:199], v143 offset:37888
	ds_read_b128 v[202:205], v143 offset:38912
	ds_read_b128 v[206:209], v143 offset:39936
	global_load_lds_dwordx4 v[220:221], off
	v_lshl_add_u64 v[220:221], s[26:27], 0, v[132:133]
	s_mov_b32 m0, s49
	s_nop 0
	global_load_lds_dwordx4 v[220:221], off
	s_waitcnt vmcnt(8)
	s_waitcnt lgkmcnt(0)
	s_barrier
	s_setprio 1
	s_waitcnt lgkmcnt(0)
	v_mfma_f32_16x16x32_bf16 v[126:129], v[144:147], v[176:179], v[126:129]
	v_mfma_f32_16x16x32_bf16 v[122:125], v[152:155], v[176:179], v[122:125]
	v_mfma_f32_16x16x32_bf16 v[118:121], v[144:147], v[184:187], v[118:121]
	v_mfma_f32_16x16x32_bf16 v[110:113], v[152:155], v[184:187], v[110:113]
	v_mfma_f32_16x16x32_bf16 v[102:105], v[144:147], v[192:195], v[102:105]
	v_mfma_f32_16x16x32_bf16 v[94:97], v[152:155], v[192:195], v[94:97]
	v_mfma_f32_16x16x32_bf16 v[86:89], v[144:147], v[202:205], v[86:89]
	v_mfma_f32_16x16x32_bf16 v[78:81], v[152:155], v[202:205], v[78:81]
	v_mfma_f32_16x16x32_bf16 v[126:129], v[148:151], v[180:183], v[126:129]
	v_mfma_f32_16x16x32_bf16 v[122:125], v[156:159], v[180:183], v[122:125]
	v_mfma_f32_16x16x32_bf16 v[118:121], v[148:151], v[188:191], v[118:121]
	v_mfma_f32_16x16x32_bf16 v[110:113], v[156:159], v[188:191], v[110:113]
	v_mfma_f32_16x16x32_bf16 v[102:105], v[148:151], v[196:199], v[102:105]
	v_mfma_f32_16x16x32_bf16 v[94:97], v[156:159], v[196:199], v[94:97]
	v_mfma_f32_16x16x32_bf16 v[86:89], v[148:151], v[206:209], v[86:89]
	v_mfma_f32_16x16x32_bf16 v[78:81], v[156:159], v[206:209], v[78:81]
	s_setprio 0
	s_setprio 1
	v_mfma_f32_16x16x32_bf16 v[114:117], v[160:163], v[176:179], v[114:117]
	v_mfma_f32_16x16x32_bf16 v[106:109], v[168:171], v[176:179], v[106:109]
	v_mfma_f32_16x16x32_bf16 v[98:101], v[160:163], v[184:187], v[98:101]
	v_mfma_f32_16x16x32_bf16 v[90:93], v[168:171], v[184:187], v[90:93]
	v_mfma_f32_16x16x32_bf16 v[82:85], v[160:163], v[192:195], v[82:85]
	v_mfma_f32_16x16x32_bf16 v[74:77], v[168:171], v[192:195], v[74:77]
	v_mfma_f32_16x16x32_bf16 v[70:73], v[160:163], v[202:205], v[70:73]
	v_mfma_f32_16x16x32_bf16 v[66:69], v[168:171], v[202:205], v[66:69]
	v_mfma_f32_16x16x32_bf16 v[114:117], v[164:167], v[180:183], v[114:117]
	v_mfma_f32_16x16x32_bf16 v[106:109], v[172:175], v[180:183], v[106:109]
	v_mfma_f32_16x16x32_bf16 v[98:101], v[164:167], v[188:191], v[98:101]
	v_mfma_f32_16x16x32_bf16 v[90:93], v[172:175], v[188:191], v[90:93]
	v_mfma_f32_16x16x32_bf16 v[82:85], v[164:167], v[196:199], v[82:85]
	v_mfma_f32_16x16x32_bf16 v[74:77], v[172:175], v[196:199], v[74:77]
	v_mfma_f32_16x16x32_bf16 v[70:73], v[164:167], v[206:209], v[70:73]
	v_mfma_f32_16x16x32_bf16 v[66:69], v[172:175], v[206:209], v[66:69]
	s_setprio 0
	s_barrier
; #define PG8_STAGE(bufoff, gbase, voff) do { _Pragma("unroll") for (int _i = 0; _i < 2; ++_i) \
;         __builtin_amdgcn_global_load_lds((const unsigned*)((const char*)(gbase) + (voff)[_i]), (PG8_LAS unsigned*)(lds + (bufoff) + ldsw + _i * 8192), 16, 0, 0); } while (0)
; #define PG8_LDA(dst, b, h) do { _Pragma("unroll") for (int m = 0; m < 4; ++m) _Pragma("unroll") for (int k = 0; k < 2; ++k) dst[m][k] = *(const PG8_LAS bf16x8*)(lds + PG8_SA(b, h) + aoff + m * 2048 + k * 1024); } while (0)
; #define PG8_MMA(ai, bj, At, Bt) do { __builtin_amdgcn_s_setprio(1); _Pragma("unroll") for (int m = 0; m < 4; ++m) _Pragma("unroll") for (int n = 0; n < 2; ++n) _Pragma("unroll") for (int k = 0; k < 2; ++k) \
;         acc[ai][bj][m][n] = __builtin_amdgcn_mfma_f32_16x16x32_bf16(Bt[n][k], At[m][k], acc[ai][bj][m][n], 0, 0, 0); __builtin_amdgcn_s_setprio(0); } while (0)
; #define PG8_WAIT_V(n) asm volatile("s_waitcnt vmcnt(" #n ")" ::: "memory")
; #define PG8_WAIT_L(n) asm volatile("s_waitcnt lgkmcnt(" #n ")" ::: "memory")
; #define PG8_BAR __builtin_amdgcn_s_barrier()
; #define PG8_SCHED __builtin_amdgcn_sched_barrier(0)
; template <class Epi, class Sched, bool ALIGN_EPI = false, bool SP2 = false>
; __device__ __forceinline__ void gemm_phase(PG8_LAS unsigned char* lds, const Gemm g, const Sched& S, const Epi& E) {
;     ...
;         for (int t = 0; t < nt; t += 2) {
;     ...
;             PG8_LDA(At, 1, 1); PG8_STAGE(PG8_SB(1, 0), b3, voffB); PG8_STAGE(PG8_SB(1, 1), b3 + hstep, voffB); PG8_STAGE(PG8_SA(1, 0), a3, voffA);
;             PG8_WAIT_V(8); PG8_WAIT_L(0); PG8_BAR; PG8_MMA(1, 0, At, B0); PG8_MMA(1, 1, At, B1); PG8_BAR; PG8_SCHED;
	s_add_i32 s26, s62, s37
	v_lshl_add_u64 v[140:141], v[140:141], 0, s[84:85]
	s_mov_b32 m0, s26
	ds_read_b128 v[176:179], v143 offset:49152
	ds_read_b128 v[180:183], v143 offset:50176
	ds_read_b128 v[184:187], v143 offset:51200
	ds_read_b128 v[188:191], v143 offset:52224
	ds_read_b128 v[192:195], v143 offset:53248
	ds_read_b128 v[196:199], v143 offset:54272
	ds_read_b128 v[202:205], v143 offset:55296
	ds_read_b128 v[206:209], v143 offset:56320
	global_load_lds_dwordx4 v[140:141], off
	s_add_i32 m0, s26, 0x2000
	s_add_u32 s24, s24, 0x80080
	v_lshl_add_u64 v[140:141], v[210:211], 0, s[84:85]
	s_addc_u32 s25, s25, 0
	s_add_i32 s26, s63, s37
	global_load_lds_dwordx4 v[140:141], off
	v_lshl_add_u64 v[140:141], s[24:25], 0, v[0:1]
	s_mov_b32 m0, s26
	s_nop 0
	global_load_lds_dwordx4 v[140:141], off
	v_lshl_add_u64 v[140:141], s[24:25], 0, v[130:131]
	s_add_i32 m0, s26, 0x2000
	s_nop 0
	global_load_lds_dwordx4 v[140:141], off
	v_lshl_add_u64 v[140:141], v[212:213], 0, s[84:85]
	s_mov_b32 m0, s52
	s_nop 0
	global_load_lds_dwordx4 v[140:141], off
	v_lshl_add_u64 v[140:141], v[218:219], 0, s[84:85]
	s_mov_b32 m0, s53
	s_nop 0
	global_load_lds_dwordx4 v[140:141], off
	s_waitcnt vmcnt(8)
	s_waitcnt lgkmcnt(0)
	s_barrier
	s_setprio 1
	s_waitcnt lgkmcnt(0)
	v_mfma_f32_16x16x32_bf16 v[62:65], v[144:147], v[176:179], v[62:65]
	v_mfma_f32_16x16x32_bf16 v[58:61], v[152:155], v[176:179], v[58:61]
	v_mfma_f32_16x16x32_bf16 v[54:57], v[144:147], v[184:187], v[54:57]
	v_mfma_f32_16x16x32_bf16 v[46:49], v[152:155], v[184:187], v[46:49]
	v_mfma_f32_16x16x32_bf16 v[38:41], v[144:147], v[192:195], v[38:41]
	v_mfma_f32_16x16x32_bf16 v[30:33], v[152:155], v[192:195], v[30:33]
	v_mfma_f32_16x16x32_bf16 v[22:25], v[144:147], v[202:205], v[22:25]
	v_mfma_f32_16x16x32_bf16 v[14:17], v[152:155], v[202:205], v[14:17]
	v_mfma_f32_16x16x32_bf16 v[62:65], v[148:151], v[180:183], v[62:65]
	v_mfma_f32_16x16x32_bf16 v[58:61], v[156:159], v[180:183], v[58:61]
	v_mfma_f32_16x16x32_bf16 v[54:57], v[148:151], v[188:191], v[54:57]
	v_mfma_f32_16x16x32_bf16 v[46:49], v[156:159], v[188:191], v[46:49]
	v_mfma_f32_16x16x32_bf16 v[38:41], v[148:151], v[196:199], v[38:41]
	v_mfma_f32_16x16x32_bf16 v[30:33], v[156:159], v[196:199], v[30:33]
	v_mfma_f32_16x16x32_bf16 v[22:25], v[148:151], v[206:209], v[22:25]
	v_mfma_f32_16x16x32_bf16 v[14:17], v[156:159], v[206:209], v[14:17]
	s_setprio 0
	s_setprio 1
	v_mfma_f32_16x16x32_bf16 v[50:53], v[160:163], v[176:179], v[50:53]
	v_mfma_f32_16x16x32_bf16 v[42:45], v[168:171], v[176:179], v[42:45]
	v_mfma_f32_16x16x32_bf16 v[34:37], v[160:163], v[184:187], v[34:37]
	v_mfma_f32_16x16x32_bf16 v[26:29], v[168:171], v[184:187], v[26:29]
	v_mfma_f32_16x16x32_bf16 v[18:21], v[160:163], v[192:195], v[18:21]
	v_mfma_f32_16x16x32_bf16 v[10:13], v[168:171], v[192:195], v[10:13]
	v_mfma_f32_16x16x32_bf16 v[6:9], v[160:163], v[202:205], v[6:9]
	v_mfma_f32_16x16x32_bf16 v[2:5], v[168:171], v[202:205], v[2:5]
	v_mfma_f32_16x16x32_bf16 v[50:53], v[164:167], v[180:183], v[50:53]
	v_mfma_f32_16x16x32_bf16 v[42:45], v[172:175], v[180:183], v[42:45]
	v_mfma_f32_16x16x32_bf16 v[34:37], v[164:167], v[188:191], v[34:37]
	v_mfma_f32_16x16x32_bf16 v[26:29], v[172:175], v[188:191], v[26:29]
	v_mfma_f32_16x16x32_bf16 v[18:21], v[164:167], v[196:199], v[18:21]
	v_mfma_f32_16x16x32_bf16 v[10:13], v[172:175], v[196:199], v[10:13]
	v_mfma_f32_16x16x32_bf16 v[6:9], v[164:167], v[206:209], v[6:9]
	v_mfma_f32_16x16x32_bf16 v[2:5], v[172:175], v[206:209], v[2:5]
	s_setprio 0
	s_add_i32 s61, s61, 2
	s_add_u32 s18, s18, 0x100
	s_addc_u32 s19, s19, 0
	s_add_u32 s59, s59, 0x100
	s_addc_u32 s60, s60, 0
	s_cmp_gt_u32 s61, 29
	s_barrier
	s_cbranch_scc0 .LBB0_1557
	s_and_b64 vcc, exec, s[8:9]
	s_cbranch_vccz .LBB0_1560
	s_barrier

; #define PG8_STAGE(bufoff, gbase, voff) do { _Pragma("unroll") for (int _i = 0; _i < 2; ++_i) \
;         __builtin_amdgcn_global_load_lds((const unsigned*)((const char*)(gbase) + (voff)[_i]), (PG8_LAS unsigned*)(lds + (bufoff) + ldsw + _i * 8192), 16, 0, 0); } while (0)
; #define PG8_LDA(dst, b, h) do { _Pragma("unroll") for (int m = 0; m < 4; ++m) _Pragma("unroll") for (int k = 0; k < 2; ++k) dst[m][k] = *(const PG8_LAS bf16x8*)(lds + PG8_SA(b, h) + aoff + m * 2048 + k * 1024); } while (0)
; #define PG8_LDB(dst, b, h) do { _Pragma("unroll") for (int n = 0; n < 2; ++n) _Pragma("unroll") for (int k = 0; k < 2; ++k) dst[n][k] = *(const PG8_LAS bf16x8*)(lds + PG8_SB(b, h) + boff + n * 2048 + k * 1024); } while (0)
; #define PG8_MMA(ai, bj, At, Bt) do { __builtin_amdgcn_s_setprio(1); _Pragma("unroll") for (int m = 0; m < 4; ++m) _Pragma("unroll") for (int n = 0; n < 2; ++n) _Pragma("unroll") for (int k = 0; k < 2; ++k) \
;         acc[ai][bj][m][n] = __builtin_amdgcn_mfma_f32_16x16x32_bf16(Bt[n][k], At[m][k], acc[ai][bj][m][n], 0, 0, 0); __builtin_amdgcn_s_setprio(0); } while (0)
; #define PG8_WAIT_V(n) asm volatile("s_waitcnt vmcnt(" #n ")" ::: "memory")
; #define PG8_BAR __builtin_amdgcn_s_barrier()
; template <class Epi, class Sched, bool ALIGN_EPI = false, bool SP2 = false>
; __device__ __forceinline__ void gemm_phase(PG8_LAS unsigned char* lds, const Gemm g, const Sched& S, const Epi& E) {
;     ...
;         for (int t = 0; t < nt; t += 2) {
;             const bool last = (t == nt - 2);
;             const char* a1 = cA + (size_t)(t + 1) * kstep;
;             const char* a2 = last ? nA : cA + (size_t)(t + 2) * kstep; const char* b2 = last ? nB : cB + (size_t)(t + 2) * kstep;
;             const char* a3 = a2 + kstep; const char* b3 = b2 + kstep;
;             if (last && has_next) S.a_ready(nxt);
;             if constexpr (SP2) {
;             PG8_LDB(B0, 0, 0); PG8_LDB(B1, 0, 1); PG8_SCHED; PG8_LDA(At, 0, 0); PG8_STAGE(PG8_SA(1, 1), a1 + hstep, voffA);
;             PG8_WAIT_V(8); PG8_WAIT_L(0); PG8_BAR; PG8_MMA(0, 0, At, B0); PG8_MMA(0, 1, At, B1); PG8_BAR; PG8_SCHED;
;             PG8_LDA(At, 0, 1); PG8_STAGE(PG8_SB(0, 0), b2, voffB); PG8_STAGE(PG8_SB(0, 1), b2 + hstep, voffB); PG8_STAGE(PG8_SA(0, 0), a2, voffA);
;             PG8_WAIT_V(8); PG8_WAIT_L(0); PG8_BAR; PG8_MMA(1, 0, At, B0); PG8_MMA(1, 1, At, B1); PG8_BAR; PG8_SCHED;
.LBB0_1717:
	s_add_u32 s36, s28, 0xfffc0080
	s_addc_u32 s37, s29, -1
	s_add_i32 s66, 0, 0x10000
	s_cmp_eq_u32 s65, 12
	s_cselect_b32 s47, s25, s37
	s_cselect_b32 s46, s61, s36
	v_add_u32_e32 v148, s66, v150
	s_cselect_b32 s37, s19, s64
	s_cselect_b32 s36, s62, s63
	s_add_i32 s68, 0, 0x14000
	ds_read_b128 v[140:143], v148
	ds_read_b128 v[144:147], v148 offset:1024
	ds_read_b128 v[152:155], v148 offset:2048
	ds_read_b128 v[156:159], v148 offset:3072
	v_add_u32_e32 v148, s68, v150
	ds_read_b128 v[160:163], v148
	ds_read_b128 v[164:167], v148 offset:1024
	ds_read_b128 v[168:171], v148 offset:2048
	ds_read_b128 v[172:175], v148 offset:3072
	v_lshl_add_u64 v[148:149], s[28:29], 0, v[136:137]
	s_add_i32 m0, s50, 0xc000
	ds_read_b128 v[176:179], v151
	ds_read_b128 v[180:183], v151 offset:1024
	ds_read_b128 v[184:187], v151 offset:2048
	ds_read_b128 v[188:191], v151 offset:3072
	ds_read_b128 v[192:195], v151 offset:4096
	ds_read_b128 v[196:199], v151 offset:5120
	ds_read_b128 v[202:205], v151 offset:6144
	ds_read_b128 v[206:209], v151 offset:7168
	global_load_lds_dwordx4 v[148:149], off
	v_lshl_add_u64 v[148:149], s[28:29], 0, v[138:139]
	s_add_i32 m0, s50, 0xe000
	s_nop 0
	global_load_lds_dwordx4 v[148:149], off
	s_waitcnt vmcnt(8)
	s_waitcnt lgkmcnt(0)
	s_barrier
	s_setprio 1
	s_waitcnt lgkmcnt(0)
	v_mfma_f32_16x16x32_bf16 v[126:129], v[140:143], v[176:179], v[126:129]
	v_mfma_f32_16x16x32_bf16 v[122:125], v[152:155], v[176:179], v[122:125]
	v_mfma_f32_16x16x32_bf16 v[110:113], v[140:143], v[184:187], v[110:113]
	v_mfma_f32_16x16x32_bf16 v[106:109], v[152:155], v[184:187], v[106:109]
	v_mfma_f32_16x16x32_bf16 v[94:97], v[140:143], v[192:195], v[94:97]
	v_mfma_f32_16x16x32_bf16 v[90:93], v[152:155], v[192:195], v[90:93]
	v_mfma_f32_16x16x32_bf16 v[78:81], v[140:143], v[202:205], v[78:81]
	v_mfma_f32_16x16x32_bf16 v[74:77], v[152:155], v[202:205], v[74:77]
	v_mfma_f32_16x16x32_bf16 v[126:129], v[144:147], v[180:183], v[126:129]
	v_mfma_f32_16x16x32_bf16 v[122:125], v[156:159], v[180:183], v[122:125]
	v_mfma_f32_16x16x32_bf16 v[110:113], v[144:147], v[188:191], v[110:113]
	v_mfma_f32_16x16x32_bf16 v[106:109], v[156:159], v[188:191], v[106:109]
	v_mfma_f32_16x16x32_bf16 v[94:97], v[144:147], v[196:199], v[94:97]
	v_mfma_f32_16x16x32_bf16 v[90:93], v[156:159], v[196:199], v[90:93]
	v_mfma_f32_16x16x32_bf16 v[78:81], v[144:147], v[206:209], v[78:81]
	v_mfma_f32_16x16x32_bf16 v[74:77], v[156:159], v[206:209], v[74:77]
	s_setprio 0
	s_setprio 1
	v_mfma_f32_16x16x32_bf16 v[118:121], v[160:163], v[176:179], v[118:121]
	v_mfma_f32_16x16x32_bf16 v[114:117], v[168:171], v[176:179], v[114:117]
	v_mfma_f32_16x16x32_bf16 v[102:105], v[160:163], v[184:187], v[102:105]
	v_mfma_f32_16x16x32_bf16 v[98:101], v[168:171], v[184:187], v[98:101]
	v_mfma_f32_16x16x32_bf16 v[86:89], v[160:163], v[192:195], v[86:89]
	v_mfma_f32_16x16x32_bf16 v[82:85], v[168:171], v[192:195], v[82:85]
	v_mfma_f32_16x16x32_bf16 v[70:73], v[160:163], v[202:205], v[70:73]
	v_mfma_f32_16x16x32_bf16 v[66:69], v[168:171], v[202:205], v[66:69]
	v_mfma_f32_16x16x32_bf16 v[118:121], v[164:167], v[180:183], v[118:121]
	v_mfma_f32_16x16x32_bf16 v[114:117], v[172:175], v[180:183], v[114:117]
	v_mfma_f32_16x16x32_bf16 v[102:105], v[164:167], v[188:191], v[102:105]
	v_mfma_f32_16x16x32_bf16 v[98:101], v[172:175], v[188:191], v[98:101]
	v_mfma_f32_16x16x32_bf16 v[86:89], v[164:167], v[196:199], v[86:89]
	v_mfma_f32_16x16x32_bf16 v[82:85], v[172:175], v[196:199], v[82:85]
	v_mfma_f32_16x16x32_bf16 v[70:73], v[164:167], v[206:209], v[70:73]
	v_mfma_f32_16x16x32_bf16 v[66:69], v[172:175], v[206:209], v[66:69]
	s_setprio 0
	s_barrier
	s_add_i32 s66, s66, s49
	v_lshl_add_u64 v[148:149], s[36:37], 0, v[0:1]
	s_mov_b32 m0, s66
	ds_read_b128 v[176:179], v151 offset:16384
	ds_read_b128 v[180:183], v151 offset:17408
	ds_read_b128 v[184:187], v151 offset:18432
	ds_read_b128 v[188:191], v151 offset:19456
	ds_read_b128 v[192:195], v151 offset:20480
	ds_read_b128 v[196:199], v151 offset:21504
	ds_read_b128 v[202:205], v151 offset:22528
	ds_read_b128 v[206:209], v151 offset:23552
	global_load_lds_dwordx4 v[148:149], off
	s_add_i32 m0, s66, 0x2000
	s_add_u32 s66, s36, 0x40000
	v_lshl_add_u64 v[210:211], s[36:37], 0, v[130:131]
	s_addc_u32 s67, s37, 0
	s_add_i32 s68, s68, s49
	global_load_lds_dwordx4 v[210:211], off
	v_lshl_add_u64 v[212:213], s[66:67], 0, v[0:1]
	s_mov_b32 m0, s68
	v_lshl_add_u64 v[218:219], s[46:47], 0, v[132:133]
	global_load_lds_dwordx4 v[212:213], off
	v_lshl_add_u64 v[212:213], s[66:67], 0, v[130:131]
	s_add_i32 m0, s68, 0x2000
	s_nop 0
	global_load_lds_dwordx4 v[212:213], off
	v_lshl_add_u64 v[212:213], s[46:47], 0, v[134:135]
	s_mov_b32 m0, s50
	s_nop 0
	global_load_lds_dwordx4 v[212:213], off
	s_mov_b32 m0, s51
	s_nop 0
	global_load_lds_dwordx4 v[218:219], off
	s_waitcnt vmcnt(8)
	s_waitcnt lgkmcnt(0)
	s_barrier
; #define PG8_STAGE(bufoff, gbase, voff) do { _Pragma("unroll") for (int _i = 0; _i < 2; ++_i) \
;         __builtin_amdgcn_global_load_lds((const unsigned*)((const char*)(gbase) + (voff)[_i]), (PG8_LAS unsigned*)(lds + (bufoff) + ldsw + _i * 8192), 16, 0, 0); } while (0)
; #define PG8_LDA(dst, b, h) do { _Pragma("unroll") for (int m = 0; m < 4; ++m) _Pragma("unroll") for (int k = 0; k < 2; ++k) dst[m][k] = *(const PG8_LAS bf16x8*)(lds + PG8_SA(b, h) + aoff + m * 2048 + k * 1024); } while (0)
; #define PG8_LDB(dst, b, h) do { _Pragma("unroll") for (int n = 0; n < 2; ++n) _Pragma("unroll") for (int k = 0; k < 2; ++k) dst[n][k] = *(const PG8_LAS bf16x8*)(lds + PG8_SB(b, h) + boff + n * 2048 + k * 1024); } while (0)
; #define PG8_MMA(ai, bj, At, Bt) do { __builtin_amdgcn_s_setprio(1); _Pragma("unroll") for (int m = 0; m < 4; ++m) _Pragma("unroll") for (int n = 0; n < 2; ++n) _Pragma("unroll") for (int k = 0; k < 2; ++k) \
;         acc[ai][bj][m][n] = __builtin_amdgcn_mfma_f32_16x16x32_bf16(Bt[n][k], At[m][k], acc[ai][bj][m][n], 0, 0, 0); __builtin_amdgcn_s_setprio(0); } while (0)
; #define PG8_WAIT_V(n) asm volatile("s_waitcnt vmcnt(" #n ")" ::: "memory")
; #define PG8_WAIT_L(n) asm volatile("s_waitcnt lgkmcnt(" #n ")" ::: "memory")
; #define PG8_BAR __builtin_amdgcn_s_barrier()
; #define PG8_SCHED __builtin_amdgcn_sched_barrier(0)
; template <class Epi, class Sched, bool ALIGN_EPI = false, bool SP2 = false>
; __device__ __forceinline__ void gemm_phase(PG8_LAS unsigned char* lds, const Gemm g, const Sched& S, const Epi& E) {
;     ...
;             PG8_WAIT_V(8); PG8_WAIT_L(0); PG8_BAR; PG8_MMA(1, 0, At, B0); PG8_MMA(1, 1, At, B1); PG8_BAR; PG8_SCHED;
;             PG8_LDB(B0, 1, 0); PG8_LDB(B1, 1, 1); PG8_SCHED; PG8_LDA(At, 1, 0); PG8_STAGE(PG8_SA(0, 1), a2 + hstep, voffA);
;             PG8_WAIT_V(8); PG8_WAIT_L(0); PG8_BAR; PG8_MMA(0, 0, At, B0); PG8_MMA(0, 1, At, B1); PG8_BAR; PG8_SCHED;
	s_setprio 1
	s_waitcnt lgkmcnt(0)
	v_mfma_f32_16x16x32_bf16 v[62:65], v[140:143], v[176:179], v[62:65]
	v_mfma_f32_16x16x32_bf16 v[58:61], v[152:155], v[176:179], v[58:61]
	v_mfma_f32_16x16x32_bf16 v[46:49], v[140:143], v[184:187], v[46:49]
	v_mfma_f32_16x16x32_bf16 v[42:45], v[152:155], v[184:187], v[42:45]
	v_mfma_f32_16x16x32_bf16 v[30:33], v[140:143], v[192:195], v[30:33]
	v_mfma_f32_16x16x32_bf16 v[26:29], v[152:155], v[192:195], v[26:29]
	v_mfma_f32_16x16x32_bf16 v[14:17], v[140:143], v[202:205], v[14:17]
	v_mfma_f32_16x16x32_bf16 v[10:13], v[152:155], v[202:205], v[10:13]
	v_mfma_f32_16x16x32_bf16 v[62:65], v[144:147], v[180:183], v[62:65]
	v_mfma_f32_16x16x32_bf16 v[58:61], v[156:159], v[180:183], v[58:61]
	v_mfma_f32_16x16x32_bf16 v[46:49], v[144:147], v[188:191], v[46:49]
	v_mfma_f32_16x16x32_bf16 v[42:45], v[156:159], v[188:191], v[42:45]
	v_mfma_f32_16x16x32_bf16 v[30:33], v[144:147], v[196:199], v[30:33]
	v_mfma_f32_16x16x32_bf16 v[26:29], v[156:159], v[196:199], v[26:29]
	v_mfma_f32_16x16x32_bf16 v[14:17], v[144:147], v[206:209], v[14:17]
	v_mfma_f32_16x16x32_bf16 v[10:13], v[156:159], v[206:209], v[10:13]
	s_setprio 0
	s_setprio 1
	v_mfma_f32_16x16x32_bf16 v[54:57], v[160:163], v[176:179], v[54:57]
	v_mfma_f32_16x16x32_bf16 v[50:53], v[168:171], v[176:179], v[50:53]
	v_mfma_f32_16x16x32_bf16 v[38:41], v[160:163], v[184:187], v[38:41]
	v_mfma_f32_16x16x32_bf16 v[34:37], v[168:171], v[184:187], v[34:37]
	v_mfma_f32_16x16x32_bf16 v[22:25], v[160:163], v[192:195], v[22:25]
	v_mfma_f32_16x16x32_bf16 v[18:21], v[168:171], v[192:195], v[18:21]
	v_mfma_f32_16x16x32_bf16 v[6:9], v[160:163], v[202:205], v[6:9]
	v_mfma_f32_16x16x32_bf16 v[2:5], v[168:171], v[202:205], v[2:5]
	v_mfma_f32_16x16x32_bf16 v[54:57], v[164:167], v[180:183], v[54:57]
	v_mfma_f32_16x16x32_bf16 v[50:53], v[172:175], v[180:183], v[50:53]
	v_mfma_f32_16x16x32_bf16 v[38:41], v[164:167], v[188:191], v[38:41]
	v_mfma_f32_16x16x32_bf16 v[34:37], v[172:175], v[188:191], v[34:37]
	v_mfma_f32_16x16x32_bf16 v[22:25], v[164:167], v[196:199], v[22:25]
	v_mfma_f32_16x16x32_bf16 v[18:21], v[172:175], v[196:199], v[18:21]
	v_mfma_f32_16x16x32_bf16 v[6:9], v[164:167], v[206:209], v[6:9]
	v_mfma_f32_16x16x32_bf16 v[2:5], v[172:175], v[206:209], v[2:5]
	s_setprio 0
	s_barrier
	s_add_i32 s66, 0, 0x18000
	s_add_i32 s67, 0, 0x1c000
	v_add_u32_e32 v156, s66, v150
	v_add_u32_e32 v172, s67, v150
	ds_read_b128 v[140:143], v156
	ds_read_b128 v[144:147], v156 offset:1024
	ds_read_b128 v[152:155], v156 offset:2048
	ds_read_b128 v[156:159], v156 offset:3072
	ds_read_b128 v[160:163], v172
	ds_read_b128 v[164:167], v172 offset:1024
	ds_read_b128 v[168:171], v172 offset:2048
	ds_read_b128 v[172:175], v172 offset:3072
	s_add_u32 s46, s46, 0x40000
	s_addc_u32 s47, s47, 0
	s_mov_b32 m0, s52
	v_lshl_add_u64 v[220:221], s[46:47], 0, v[134:135]
	ds_read_b128 v[176:179], v151 offset:32768
	ds_read_b128 v[180:183], v151 offset:33792
	ds_read_b128 v[184:187], v151 offset:34816
	ds_read_b128 v[188:191], v151 offset:35840
	ds_read_b128 v[192:195], v151 offset:36864
	ds_read_b128 v[196:199], v151 offset:37888
	ds_read_b128 v[202:205], v151 offset:38912
	ds_read_b128 v[206:209], v151 offset:39936
	global_load_lds_dwordx4 v[220:221], off
	v_lshl_add_u64 v[220:221], s[46:47], 0, v[132:133]
	s_mov_b32 m0, s53
	s_nop 0
	global_load_lds_dwordx4 v[220:221], off
	s_waitcnt vmcnt(8)
	s_waitcnt lgkmcnt(0)
	s_barrier
	s_setprio 1
	s_waitcnt lgkmcnt(0)
	v_mfma_f32_16x16x32_bf16 v[126:129], v[140:143], v[176:179], v[126:129]
	v_mfma_f32_16x16x32_bf16 v[122:125], v[152:155], v[176:179], v[122:125]
	v_mfma_f32_16x16x32_bf16 v[110:113], v[140:143], v[184:187], v[110:113]
	v_mfma_f32_16x16x32_bf16 v[106:109], v[152:155], v[184:187], v[106:109]
	v_mfma_f32_16x16x32_bf16 v[94:97], v[140:143], v[192:195], v[94:97]
	v_mfma_f32_16x16x32_bf16 v[90:93], v[152:155], v[192:195], v[90:93]
	v_mfma_f32_16x16x32_bf16 v[78:81], v[140:143], v[202:205], v[78:81]
	v_mfma_f32_16x16x32_bf16 v[74:77], v[152:155], v[202:205], v[74:77]
	v_mfma_f32_16x16x32_bf16 v[126:129], v[144:147], v[180:183], v[126:129]
	v_mfma_f32_16x16x32_bf16 v[122:125], v[156:159], v[180:183], v[122:125]
	v_mfma_f32_16x16x32_bf16 v[110:113], v[144:147], v[188:191], v[110:113]
	v_mfma_f32_16x16x32_bf16 v[106:109], v[156:159], v[188:191], v[106:109]
	v_mfma_f32_16x16x32_bf16 v[94:97], v[144:147], v[196:199], v[94:97]
	v_mfma_f32_16x16x32_bf16 v[90:93], v[156:159], v[196:199], v[90:93]
	v_mfma_f32_16x16x32_bf16 v[78:81], v[144:147], v[206:209], v[78:81]
	v_mfma_f32_16x16x32_bf16 v[74:77], v[156:159], v[206:209], v[74:77]
	s_setprio 0
	s_setprio 1
	v_mfma_f32_16x16x32_bf16 v[118:121], v[160:163], v[176:179], v[118:121]
	v_mfma_f32_16x16x32_bf16 v[114:117], v[168:171], v[176:179], v[114:117]
	v_mfma_f32_16x16x32_bf16 v[102:105], v[160:163], v[184:187], v[102:105]
	v_mfma_f32_16x16x32_bf16 v[98:101], v[168:171], v[184:187], v[98:101]
	v_mfma_f32_16x16x32_bf16 v[86:89], v[160:163], v[192:195], v[86:89]
	v_mfma_f32_16x16x32_bf16 v[82:85], v[168:171], v[192:195], v[82:85]
	v_mfma_f32_16x16x32_bf16 v[70:73], v[160:163], v[202:205], v[70:73]
	v_mfma_f32_16x16x32_bf16 v[66:69], v[168:171], v[202:205], v[66:69]
	v_mfma_f32_16x16x32_bf16 v[118:121], v[164:167], v[180:183], v[118:121]
	v_mfma_f32_16x16x32_bf16 v[114:117], v[172:175], v[180:183], v[114:117]
	v_mfma_f32_16x16x32_bf16 v[102:105], v[164:167], v[188:191], v[102:105]
	v_mfma_f32_16x16x32_bf16 v[98:101], v[172:175], v[188:191], v[98:101]
	v_mfma_f32_16x16x32_bf16 v[86:89], v[164:167], v[196:199], v[86:89]
	v_mfma_f32_16x16x32_bf16 v[82:85], v[172:175], v[196:199], v[82:85]
	v_mfma_f32_16x16x32_bf16 v[70:73], v[164:167], v[206:209], v[70:73]
	v_mfma_f32_16x16x32_bf16 v[66:69], v[172:175], v[206:209], v[66:69]
	s_setprio 0
	s_barrier
; #define PG8_STAGE(bufoff, gbase, voff) do { _Pragma("unroll") for (int _i = 0; _i < 2; ++_i) \
;         __builtin_amdgcn_global_load_lds((const unsigned*)((const char*)(gbase) + (voff)[_i]), (PG8_LAS unsigned*)(lds + (bufoff) + ldsw + _i * 8192), 16, 0, 0); } while (0)
; #define PG8_LDA(dst, b, h) do { _Pragma("unroll") for (int m = 0; m < 4; ++m) _Pragma("unroll") for (int k = 0; k < 2; ++k) dst[m][k] = *(const PG8_LAS bf16x8*)(lds + PG8_SA(b, h) + aoff + m * 2048 + k * 1024); } while (0)
; #define PG8_MMA(ai, bj, At, Bt) do { __builtin_amdgcn_s_setprio(1); _Pragma("unroll") for (int m = 0; m < 4; ++m) _Pragma("unroll") for (int n = 0; n < 2; ++n) _Pragma("unroll") for (int k = 0; k < 2; ++k) \
;         acc[ai][bj][m][n] = __builtin_amdgcn_mfma_f32_16x16x32_bf16(Bt[n][k], At[m][k], acc[ai][bj][m][n], 0, 0, 0); __builtin_amdgcn_s_setprio(0); } while (0)
; #define PG8_WAIT_V(n) asm volatile("s_waitcnt vmcnt(" #n ")" ::: "memory")
; #define PG8_WAIT_L(n) asm volatile("s_waitcnt lgkmcnt(" #n ")" ::: "memory")
; #define PG8_BAR __builtin_amdgcn_s_barrier()
; #define PG8_SCHED __builtin_amdgcn_sched_barrier(0)
; template <class Epi, class Sched, bool ALIGN_EPI = false, bool SP2 = false>
; __device__ __forceinline__ void gemm_phase(PG8_LAS unsigned char* lds, const Gemm g, const Sched& S, const Epi& E) {
;     ...
;         for (int t = 0; t < nt; t += 2) {
;     ...
;             PG8_LDA(At, 1, 1); PG8_STAGE(PG8_SB(1, 0), b3, voffB); PG8_STAGE(PG8_SB(1, 1), b3 + hstep, voffB); PG8_STAGE(PG8_SA(1, 0), a3, voffA);
;             PG8_WAIT_V(8); PG8_WAIT_L(0); PG8_BAR; PG8_MMA(1, 0, At, B0); PG8_MMA(1, 1, At, B1); PG8_BAR; PG8_SCHED;
	s_add_i32 s46, s66, s49
	v_lshl_add_u64 v[148:149], v[148:149], 0, s[84:85]
	s_mov_b32 m0, s46
	ds_read_b128 v[176:179], v151 offset:49152
	ds_read_b128 v[180:183], v151 offset:50176
	ds_read_b128 v[184:187], v151 offset:51200
	ds_read_b128 v[188:191], v151 offset:52224
	ds_read_b128 v[192:195], v151 offset:53248
	ds_read_b128 v[196:199], v151 offset:54272
	ds_read_b128 v[202:205], v151 offset:55296
	ds_read_b128 v[206:209], v151 offset:56320
	global_load_lds_dwordx4 v[148:149], off
	s_add_i32 m0, s46, 0x2000
	s_add_u32 s36, s36, 0x40080
	v_lshl_add_u64 v[148:149], v[210:211], 0, s[84:85]
	s_addc_u32 s37, s37, 0
	s_add_i32 s46, s67, s49
	global_load_lds_dwordx4 v[148:149], off
	v_lshl_add_u64 v[148:149], s[36:37], 0, v[0:1]
	s_mov_b32 m0, s46
	s_nop 0
	global_load_lds_dwordx4 v[148:149], off
	v_lshl_add_u64 v[148:149], s[36:37], 0, v[130:131]
	s_add_i32 m0, s46, 0x2000
	s_nop 0
	global_load_lds_dwordx4 v[148:149], off
	v_lshl_add_u64 v[148:149], v[212:213], 0, s[84:85]
	s_mov_b32 m0, s56
	s_nop 0
	global_load_lds_dwordx4 v[148:149], off
	v_lshl_add_u64 v[148:149], v[218:219], 0, s[84:85]
	s_mov_b32 m0, s57
	s_nop 0
	global_load_lds_dwordx4 v[148:149], off
	s_waitcnt vmcnt(8)
	s_waitcnt lgkmcnt(0)
	s_barrier
	s_setprio 1
	s_waitcnt lgkmcnt(0)
	v_mfma_f32_16x16x32_bf16 v[62:65], v[140:143], v[176:179], v[62:65]
	v_mfma_f32_16x16x32_bf16 v[58:61], v[152:155], v[176:179], v[58:61]
	v_mfma_f32_16x16x32_bf16 v[46:49], v[140:143], v[184:187], v[46:49]
	v_mfma_f32_16x16x32_bf16 v[42:45], v[152:155], v[184:187], v[42:45]
	v_mfma_f32_16x16x32_bf16 v[30:33], v[140:143], v[192:195], v[30:33]
	v_mfma_f32_16x16x32_bf16 v[26:29], v[152:155], v[192:195], v[26:29]
	v_mfma_f32_16x16x32_bf16 v[14:17], v[140:143], v[202:205], v[14:17]
	v_mfma_f32_16x16x32_bf16 v[10:13], v[152:155], v[202:205], v[10:13]
	v_mfma_f32_16x16x32_bf16 v[62:65], v[144:147], v[180:183], v[62:65]
	v_mfma_f32_16x16x32_bf16 v[58:61], v[156:159], v[180:183], v[58:61]
	v_mfma_f32_16x16x32_bf16 v[46:49], v[144:147], v[188:191], v[46:49]
	v_mfma_f32_16x16x32_bf16 v[42:45], v[156:159], v[188:191], v[42:45]
	v_mfma_f32_16x16x32_bf16 v[30:33], v[144:147], v[196:199], v[30:33]
	v_mfma_f32_16x16x32_bf16 v[26:29], v[156:159], v[196:199], v[26:29]
	v_mfma_f32_16x16x32_bf16 v[14:17], v[144:147], v[206:209], v[14:17]
	v_mfma_f32_16x16x32_bf16 v[10:13], v[156:159], v[206:209], v[10:13]
	s_setprio 0
	s_setprio 1
	v_mfma_f32_16x16x32_bf16 v[54:57], v[160:163], v[176:179], v[54:57]
	v_mfma_f32_16x16x32_bf16 v[50:53], v[168:171], v[176:179], v[50:53]
	v_mfma_f32_16x16x32_bf16 v[38:41], v[160:163], v[184:187], v[38:41]
	v_mfma_f32_16x16x32_bf16 v[34:37], v[168:171], v[184:187], v[34:37]
	v_mfma_f32_16x16x32_bf16 v[22:25], v[160:163], v[192:195], v[22:25]
	v_mfma_f32_16x16x32_bf16 v[18:21], v[168:171], v[192:195], v[18:21]
	v_mfma_f32_16x16x32_bf16 v[6:9], v[160:163], v[202:205], v[6:9]
	v_mfma_f32_16x16x32_bf16 v[2:5], v[168:171], v[202:205], v[2:5]
	v_mfma_f32_16x16x32_bf16 v[54:57], v[164:167], v[180:183], v[54:57]
	v_mfma_f32_16x16x32_bf16 v[50:53], v[172:175], v[180:183], v[50:53]
	v_mfma_f32_16x16x32_bf16 v[38:41], v[164:167], v[188:191], v[38:41]
	v_mfma_f32_16x16x32_bf16 v[34:37], v[172:175], v[188:191], v[34:37]
	v_mfma_f32_16x16x32_bf16 v[22:25], v[164:167], v[196:199], v[22:25]
	v_mfma_f32_16x16x32_bf16 v[18:21], v[172:175], v[196:199], v[18:21]
	v_mfma_f32_16x16x32_bf16 v[6:9], v[164:167], v[206:209], v[6:9]
	v_mfma_f32_16x16x32_bf16 v[2:5], v[172:175], v[206:209], v[2:5]
	s_setprio 0
	s_add_i32 s65, s65, 2
	s_add_u32 s28, s28, 0x100
	s_addc_u32 s29, s29, 0
	s_add_u32 s63, s63, 0x100
	s_addc_u32 s64, s64, 0
	s_cmp_gt_u32 s65, 13
	s_barrier
	s_cbranch_scc0 .LBB0_1717
	s_and_b64 vcc, exec, s[16:17]
	s_cbranch_vccz .LBB0_1720
	s_barrier
